# GEMM K-loops: all per-segment s_setprio removed (plus redundant head lgkmcnt waits removed, pipelined census loads)
# speedup vs baseline: 1.0096x; 1.0042x over previous
; #define PG8_STAGE(bufoff, gbase, voff) do { _Pragma("unroll") for (int _i = 0; _i < 2; ++_i) \
;         __builtin_amdgcn_global_load_lds((const unsigned*)((const char*)(gbase) + (voff)[_i]), (PG8_LAS unsigned*)(lds + (bufoff) + ldsw + _i * 8192), 16, 0, 0); } while (0)
; #define PG8_LDA(dst, b, h) do { _Pragma("unroll") for (int m = 0; m < 4; ++m) _Pragma("unroll") for (int k = 0; k < 2; ++k) dst[m][k] = *(const PG8_LAS bf16x8*)(lds + PG8_SA(b, h) + aoff + m * 2048 + k * 1024); } while (0)
; #define PG8_LDB(dst, b, h) do { _Pragma("unroll") for (int n = 0; n < 2; ++n) _Pragma("unroll") for (int k = 0; k < 2; ++k) dst[n][k] = *(const PG8_LAS bf16x8*)(lds + PG8_SB(b, h) + boff + n * 2048 + k * 1024); } while (0)
; #define PG8_MMA(ai, bj, At, Bt) do { __builtin_amdgcn_s_setprio(1); _Pragma("unroll") for (int m = 0; m < 4; ++m) _Pragma("unroll") for (int n = 0; n < 2; ++n) _Pragma("unroll") for (int k = 0; k < 2; ++k) \
;         acc[ai][bj][m][n] = __builtin_amdgcn_mfma_f32_16x16x32_bf16(Bt[n][k], At[m][k], acc[ai][bj][m][n], 0, 0, 0); __builtin_amdgcn_s_setprio(0); } while (0)
; #define PG8_WAIT_V(n) asm volatile("s_waitcnt vmcnt(" #n ")" ::: "memory")
; #define PG8_WAIT_L(n) asm volatile("s_waitcnt lgkmcnt(" #n ")" ::: "memory")
; #define PG8_BAR __builtin_amdgcn_s_barrier()
; #define PG8_SCHED __builtin_amdgcn_sched_barrier(0)
; template <class Epi, class Sched, bool ALIGN_EPI = false, bool SP2 = false>
; __device__ __forceinline__ void gemm_phase(PG8_LAS unsigned char* lds, const Gemm g, const Sched& S, const Epi& E) {
;     ...
;             PG8_LDB(B0, 0, 0); PG8_LDB(B1, 0, 1); PG8_SCHED; PG8_LDA(At, 0, 0); PG8_STAGE(PG8_SA(1, 1), a1 + hstep, voffA);
;             PG8_WAIT_V(8); PG8_WAIT_L(0); PG8_BAR; PG8_MMA(0, 0, At, B0); PG8_MMA(0, 1, At, B1); PG8_BAR; PG8_SCHED;
;             PG8_LDA(At, 0, 1); PG8_STAGE(PG8_SB(0, 0), b2, voffB); PG8_STAGE(PG8_SB(0, 1), b2 + hstep, voffB); PG8_STAGE(PG8_SA(0, 0), a2, voffA);
.LBB0_265:
	s_add_u32 s10, s16, 0xfff80080
	s_addc_u32 s11, s17, -1
	s_add_i32 s27, 0, 0x10000
	s_cmp_eq_u32 s23, 28
	s_cselect_b32 s51, s5, s11
	s_cselect_b32 s50, s7, s10
	s_cselect_b32 s19, s8, s22
	s_cselect_b32 s18, s9, s15
	s_add_i32 s10, 0, 0x14000
	v_add_u32_e32 v168, s27, v157
	v_add_u32_e32 v184, s10, v157
	ds_read_b128 v[152:155], v168
	ds_read_b128 v[160:163], v168 offset:1024
	ds_read_b128 v[164:167], v168 offset:2048
	ds_read_b128 v[168:171], v168 offset:3072
	ds_read_b128 v[172:175], v184
	ds_read_b128 v[176:179], v184 offset:1024
	ds_read_b128 v[180:183], v184 offset:2048
	ds_read_b128 v[184:187], v184 offset:3072
	v_lshl_add_u64 v[200:201], s[16:17], 0, v[148:149]
	s_add_i32 m0, s57, 0xc000
	ds_read_b128 v[188:191], v159
	ds_read_b128 v[192:195], v159 offset:1024
	ds_read_b128 v[196:199], v159 offset:2048
	ds_read_b128 v[216:219], v159 offset:3072
	ds_read_b128 v[220:223], v159 offset:4096
	ds_read_b128 v[224:227], v159 offset:5120
	ds_read_b128 v[228:231], v159 offset:6144
	ds_read_b128 v[232:235], v159 offset:7168
	global_load_lds_dwordx4 v[200:201], off
	v_lshl_add_u64 v[200:201], s[16:17], 0, v[150:151]
	s_add_i32 m0, s57, 0xe000
	s_nop 0
	global_load_lds_dwordx4 v[200:201], off
	s_waitcnt vmcnt(8)
	s_waitcnt lgkmcnt(0)
	s_barrier
	v_mfma_f32_16x16x32_bf16 v[126:129], v[152:155], v[188:191], v[126:129]
	v_mfma_f32_16x16x32_bf16 v[122:125], v[164:167], v[188:191], v[122:125]
	v_mfma_f32_16x16x32_bf16 v[110:113], v[152:155], v[196:199], v[110:113]
	v_mfma_f32_16x16x32_bf16 v[106:109], v[164:167], v[196:199], v[106:109]
	v_mfma_f32_16x16x32_bf16 v[94:97], v[152:155], v[220:223], v[94:97]
	v_mfma_f32_16x16x32_bf16 v[90:93], v[164:167], v[220:223], v[90:93]
	v_mfma_f32_16x16x32_bf16 v[78:81], v[152:155], v[228:231], v[78:81]
	v_mfma_f32_16x16x32_bf16 v[74:77], v[164:167], v[228:231], v[74:77]
	v_mfma_f32_16x16x32_bf16 v[126:129], v[160:163], v[192:195], v[126:129]
	v_mfma_f32_16x16x32_bf16 v[122:125], v[168:171], v[192:195], v[122:125]
	v_mfma_f32_16x16x32_bf16 v[110:113], v[160:163], v[216:219], v[110:113]
	v_mfma_f32_16x16x32_bf16 v[106:109], v[168:171], v[216:219], v[106:109]
	v_mfma_f32_16x16x32_bf16 v[94:97], v[160:163], v[224:227], v[94:97]
	v_mfma_f32_16x16x32_bf16 v[90:93], v[168:171], v[224:227], v[90:93]
	v_mfma_f32_16x16x32_bf16 v[78:81], v[160:163], v[232:235], v[78:81]
	v_mfma_f32_16x16x32_bf16 v[74:77], v[168:171], v[232:235], v[74:77]
	v_mfma_f32_16x16x32_bf16 v[118:121], v[172:175], v[188:191], v[118:121]
	v_mfma_f32_16x16x32_bf16 v[114:117], v[180:183], v[188:191], v[114:117]
	v_mfma_f32_16x16x32_bf16 v[102:105], v[172:175], v[196:199], v[102:105]
	v_mfma_f32_16x16x32_bf16 v[98:101], v[180:183], v[196:199], v[98:101]
	v_mfma_f32_16x16x32_bf16 v[86:89], v[172:175], v[220:223], v[86:89]
	v_mfma_f32_16x16x32_bf16 v[82:85], v[180:183], v[220:223], v[82:85]
	v_mfma_f32_16x16x32_bf16 v[70:73], v[172:175], v[228:231], v[70:73]
	v_mfma_f32_16x16x32_bf16 v[66:69], v[180:183], v[228:231], v[66:69]
	v_mfma_f32_16x16x32_bf16 v[118:121], v[176:179], v[192:195], v[118:121]
	v_mfma_f32_16x16x32_bf16 v[114:117], v[184:187], v[192:195], v[114:117]
	v_mfma_f32_16x16x32_bf16 v[102:105], v[176:179], v[216:219], v[102:105]
	v_mfma_f32_16x16x32_bf16 v[98:101], v[184:187], v[216:219], v[98:101]
	v_mfma_f32_16x16x32_bf16 v[86:89], v[176:179], v[224:227], v[86:89]
	v_mfma_f32_16x16x32_bf16 v[82:85], v[184:187], v[224:227], v[82:85]
	v_mfma_f32_16x16x32_bf16 v[70:73], v[176:179], v[232:235], v[70:73]
	v_mfma_f32_16x16x32_bf16 v[66:69], v[184:187], v[232:235], v[66:69]
	s_barrier
	s_add_i32 s11, s27, s56
	v_lshl_add_u64 v[200:201], s[18:19], 0, v[0:1]
	s_mov_b32 m0, s11
	ds_read_b128 v[188:191], v159 offset:16384
	ds_read_b128 v[192:195], v159 offset:17408
	ds_read_b128 v[196:199], v159 offset:18432
	ds_read_b128 v[216:219], v159 offset:19456
	ds_read_b128 v[220:223], v159 offset:20480
	ds_read_b128 v[224:227], v159 offset:21504
	ds_read_b128 v[228:231], v159 offset:22528
	ds_read_b128 v[232:235], v159 offset:23552
	global_load_lds_dwordx4 v[200:201], off
	s_add_i32 m0, s11, 0x2000
	s_add_u32 s38, s18, 0x80000
	v_lshl_add_u64 v[236:237], s[18:19], 0, v[142:143]
	s_addc_u32 s39, s19, 0
	s_add_i32 s10, s10, s56
	global_load_lds_dwordx4 v[236:237], off
	v_lshl_add_u64 v[238:239], s[38:39], 0, v[0:1]
	s_mov_b32 m0, s10
	v_lshl_add_u64 v[240:241], s[50:51], 0, v[144:145]
	global_load_lds_dwordx4 v[238:239], off
	v_lshl_add_u64 v[238:239], s[38:39], 0, v[142:143]
	s_add_i32 m0, s10, 0x2000
	s_nop 0
	global_load_lds_dwordx4 v[238:239], off
	v_lshl_add_u64 v[238:239], s[50:51], 0, v[146:147]
	s_mov_b32 m0, s57
	s_nop 0
	global_load_lds_dwordx4 v[238:239], off
	s_mov_b32 m0, s58
	s_nop 0
	global_load_lds_dwordx4 v[240:241], off
	s_waitcnt vmcnt(8)
	s_waitcnt lgkmcnt(0)
	s_barrier
; #define PG8_STAGE(bufoff, gbase, voff) do { _Pragma("unroll") for (int _i = 0; _i < 2; ++_i) \
;         __builtin_amdgcn_global_load_lds((const unsigned*)((const char*)(gbase) + (voff)[_i]), (PG8_LAS unsigned*)(lds + (bufoff) + ldsw + _i * 8192), 16, 0, 0); } while (0)
; #define PG8_LDA(dst, b, h) do { _Pragma("unroll") for (int m = 0; m < 4; ++m) _Pragma("unroll") for (int k = 0; k < 2; ++k) dst[m][k] = *(const PG8_LAS bf16x8*)(lds + PG8_SA(b, h) + aoff + m * 2048 + k * 1024); } while (0)
; #define PG8_LDB(dst, b, h) do { _Pragma("unroll") for (int n = 0; n < 2; ++n) _Pragma("unroll") for (int k = 0; k < 2; ++k) dst[n][k] = *(const PG8_LAS bf16x8*)(lds + PG8_SB(b, h) + boff + n * 2048 + k * 1024); } while (0)
; #define PG8_MMA(ai, bj, At, Bt) do { __builtin_amdgcn_s_setprio(1); _Pragma("unroll") for (int m = 0; m < 4; ++m) _Pragma("unroll") for (int n = 0; n < 2; ++n) _Pragma("unroll") for (int k = 0; k < 2; ++k) \
;         acc[ai][bj][m][n] = __builtin_amdgcn_mfma_f32_16x16x32_bf16(Bt[n][k], At[m][k], acc[ai][bj][m][n], 0, 0, 0); __builtin_amdgcn_s_setprio(0); } while (0)
; #define PG8_WAIT_V(n) asm volatile("s_waitcnt vmcnt(" #n ")" ::: "memory")
; #define PG8_WAIT_L(n) asm volatile("s_waitcnt lgkmcnt(" #n ")" ::: "memory")
; #define PG8_BAR __builtin_amdgcn_s_barrier()
; #define PG8_SCHED __builtin_amdgcn_sched_barrier(0)
; template <class Epi, class Sched, bool ALIGN_EPI = false, bool SP2 = false>
; __device__ __forceinline__ void gemm_phase(PG8_LAS unsigned char* lds, const Gemm g, const Sched& S, const Epi& E) {
;     ...
;             PG8_WAIT_V(8); PG8_WAIT_L(0); PG8_BAR; PG8_MMA(1, 0, At, B0); PG8_MMA(1, 1, At, B1); PG8_BAR; PG8_SCHED;
;             PG8_LDB(B0, 1, 0); PG8_LDB(B1, 1, 1); PG8_SCHED; PG8_LDA(At, 1, 0); PG8_STAGE(PG8_SA(0, 1), a2 + hstep, voffA);
;             PG8_WAIT_V(8); PG8_WAIT_L(0); PG8_BAR; PG8_MMA(0, 0, At, B0); PG8_MMA(0, 1, At, B1); PG8_BAR; PG8_SCHED;
	v_mfma_f32_16x16x32_bf16 v[62:65], v[152:155], v[188:191], v[62:65]
	v_mfma_f32_16x16x32_bf16 v[58:61], v[164:167], v[188:191], v[58:61]
	v_mfma_f32_16x16x32_bf16 v[50:53], v[152:155], v[196:199], v[50:53]
	v_mfma_f32_16x16x32_bf16 v[42:45], v[164:167], v[196:199], v[42:45]
	v_mfma_f32_16x16x32_bf16 v[34:37], v[152:155], v[220:223], v[34:37]
	v_mfma_f32_16x16x32_bf16 v[26:29], v[164:167], v[220:223], v[26:29]
	v_mfma_f32_16x16x32_bf16 v[18:21], v[152:155], v[228:231], v[18:21]
	v_mfma_f32_16x16x32_bf16 v[10:13], v[164:167], v[228:231], v[10:13]
	v_mfma_f32_16x16x32_bf16 v[62:65], v[160:163], v[192:195], v[62:65]
	v_mfma_f32_16x16x32_bf16 v[58:61], v[168:171], v[192:195], v[58:61]
	v_mfma_f32_16x16x32_bf16 v[50:53], v[160:163], v[216:219], v[50:53]
	v_mfma_f32_16x16x32_bf16 v[42:45], v[168:171], v[216:219], v[42:45]
	v_mfma_f32_16x16x32_bf16 v[34:37], v[160:163], v[224:227], v[34:37]
	v_mfma_f32_16x16x32_bf16 v[26:29], v[168:171], v[224:227], v[26:29]
	v_mfma_f32_16x16x32_bf16 v[18:21], v[160:163], v[232:235], v[18:21]
	v_mfma_f32_16x16x32_bf16 v[10:13], v[168:171], v[232:235], v[10:13]
	v_mfma_f32_16x16x32_bf16 v[54:57], v[172:175], v[188:191], v[54:57]
	v_mfma_f32_16x16x32_bf16 v[46:49], v[180:183], v[188:191], v[46:49]
	v_mfma_f32_16x16x32_bf16 v[38:41], v[172:175], v[196:199], v[38:41]
	v_mfma_f32_16x16x32_bf16 v[30:33], v[180:183], v[196:199], v[30:33]
	v_mfma_f32_16x16x32_bf16 v[22:25], v[172:175], v[220:223], v[22:25]
	v_mfma_f32_16x16x32_bf16 v[14:17], v[180:183], v[220:223], v[14:17]
	v_mfma_f32_16x16x32_bf16 v[6:9], v[172:175], v[228:231], v[6:9]
	v_mfma_f32_16x16x32_bf16 v[2:5], v[180:183], v[228:231], v[2:5]
	v_mfma_f32_16x16x32_bf16 v[54:57], v[176:179], v[192:195], v[54:57]
	v_mfma_f32_16x16x32_bf16 v[46:49], v[184:187], v[192:195], v[46:49]
	v_mfma_f32_16x16x32_bf16 v[38:41], v[176:179], v[216:219], v[38:41]
	v_mfma_f32_16x16x32_bf16 v[30:33], v[184:187], v[216:219], v[30:33]
	v_mfma_f32_16x16x32_bf16 v[22:25], v[176:179], v[224:227], v[22:25]
	v_mfma_f32_16x16x32_bf16 v[14:17], v[184:187], v[224:227], v[14:17]
	v_mfma_f32_16x16x32_bf16 v[6:9], v[176:179], v[232:235], v[6:9]
	v_mfma_f32_16x16x32_bf16 v[2:5], v[184:187], v[232:235], v[2:5]
	s_barrier
	s_add_i32 s10, 0, 0x18000
	s_add_i32 s11, 0, 0x1c000
	v_add_u32_e32 v168, s10, v157
	v_add_u32_e32 v184, s11, v157
	ds_read_b128 v[152:155], v168
	ds_read_b128 v[160:163], v168 offset:1024
	ds_read_b128 v[164:167], v168 offset:2048
	ds_read_b128 v[168:171], v168 offset:3072
	ds_read_b128 v[172:175], v184
	ds_read_b128 v[176:179], v184 offset:1024
	ds_read_b128 v[180:183], v184 offset:2048
	ds_read_b128 v[184:187], v184 offset:3072
	s_add_u32 s38, s50, 0x80000
	s_addc_u32 s39, s51, 0
	s_mov_b32 m0, s59
	v_lshl_add_u64 v[242:243], s[38:39], 0, v[146:147]
	ds_read_b128 v[188:191], v159 offset:32768
	ds_read_b128 v[192:195], v159 offset:33792
	ds_read_b128 v[196:199], v159 offset:34816
	ds_read_b128 v[216:219], v159 offset:35840
	ds_read_b128 v[220:223], v159 offset:36864
	ds_read_b128 v[224:227], v159 offset:37888
	ds_read_b128 v[228:231], v159 offset:38912
	ds_read_b128 v[232:235], v159 offset:39936
	global_load_lds_dwordx4 v[242:243], off
	v_lshl_add_u64 v[242:243], s[38:39], 0, v[144:145]
	s_mov_b32 m0, s60
	s_nop 0
	global_load_lds_dwordx4 v[242:243], off
	s_waitcnt vmcnt(8)
	s_waitcnt lgkmcnt(0)
	s_barrier
	v_mfma_f32_16x16x32_bf16 v[126:129], v[152:155], v[188:191], v[126:129]
	v_mfma_f32_16x16x32_bf16 v[122:125], v[164:167], v[188:191], v[122:125]
	v_mfma_f32_16x16x32_bf16 v[110:113], v[152:155], v[196:199], v[110:113]
	v_mfma_f32_16x16x32_bf16 v[106:109], v[164:167], v[196:199], v[106:109]
	v_mfma_f32_16x16x32_bf16 v[94:97], v[152:155], v[220:223], v[94:97]
	v_mfma_f32_16x16x32_bf16 v[90:93], v[164:167], v[220:223], v[90:93]
	v_mfma_f32_16x16x32_bf16 v[78:81], v[152:155], v[228:231], v[78:81]
	v_mfma_f32_16x16x32_bf16 v[74:77], v[164:167], v[228:231], v[74:77]
	v_mfma_f32_16x16x32_bf16 v[126:129], v[160:163], v[192:195], v[126:129]
	v_mfma_f32_16x16x32_bf16 v[122:125], v[168:171], v[192:195], v[122:125]
	v_mfma_f32_16x16x32_bf16 v[110:113], v[160:163], v[216:219], v[110:113]
	v_mfma_f32_16x16x32_bf16 v[106:109], v[168:171], v[216:219], v[106:109]
	v_mfma_f32_16x16x32_bf16 v[94:97], v[160:163], v[224:227], v[94:97]
	v_mfma_f32_16x16x32_bf16 v[90:93], v[168:171], v[224:227], v[90:93]
	v_mfma_f32_16x16x32_bf16 v[78:81], v[160:163], v[232:235], v[78:81]
	v_mfma_f32_16x16x32_bf16 v[74:77], v[168:171], v[232:235], v[74:77]
	v_mfma_f32_16x16x32_bf16 v[118:121], v[172:175], v[188:191], v[118:121]
	v_mfma_f32_16x16x32_bf16 v[114:117], v[180:183], v[188:191], v[114:117]
	v_mfma_f32_16x16x32_bf16 v[102:105], v[172:175], v[196:199], v[102:105]
	v_mfma_f32_16x16x32_bf16 v[98:101], v[180:183], v[196:199], v[98:101]
	v_mfma_f32_16x16x32_bf16 v[86:89], v[172:175], v[220:223], v[86:89]
	v_mfma_f32_16x16x32_bf16 v[82:85], v[180:183], v[220:223], v[82:85]
	v_mfma_f32_16x16x32_bf16 v[70:73], v[172:175], v[228:231], v[70:73]
	v_mfma_f32_16x16x32_bf16 v[66:69], v[180:183], v[228:231], v[66:69]
	v_mfma_f32_16x16x32_bf16 v[118:121], v[176:179], v[192:195], v[118:121]
	v_mfma_f32_16x16x32_bf16 v[114:117], v[184:187], v[192:195], v[114:117]
	v_mfma_f32_16x16x32_bf16 v[102:105], v[176:179], v[216:219], v[102:105]
	v_mfma_f32_16x16x32_bf16 v[98:101], v[184:187], v[216:219], v[98:101]
	v_mfma_f32_16x16x32_bf16 v[86:89], v[176:179], v[224:227], v[86:89]
	v_mfma_f32_16x16x32_bf16 v[82:85], v[184:187], v[224:227], v[82:85]
	v_mfma_f32_16x16x32_bf16 v[70:73], v[176:179], v[232:235], v[70:73]
	v_mfma_f32_16x16x32_bf16 v[66:69], v[184:187], v[232:235], v[66:69]
	s_barrier
; #define PG8_STAGE(bufoff, gbase, voff) do { _Pragma("unroll") for (int _i = 0; _i < 2; ++_i) \
;         __builtin_amdgcn_global_load_lds((const unsigned*)((const char*)(gbase) + (voff)[_i]), (PG8_LAS unsigned*)(lds + (bufoff) + ldsw + _i * 8192), 16, 0, 0); } while (0)
; #define PG8_LDA(dst, b, h) do { _Pragma("unroll") for (int m = 0; m < 4; ++m) _Pragma("unroll") for (int k = 0; k < 2; ++k) dst[m][k] = *(const PG8_LAS bf16x8*)(lds + PG8_SA(b, h) + aoff + m * 2048 + k * 1024); } while (0)
; #define PG8_MMA(ai, bj, At, Bt) do { __builtin_amdgcn_s_setprio(1); _Pragma("unroll") for (int m = 0; m < 4; ++m) _Pragma("unroll") for (int n = 0; n < 2; ++n) _Pragma("unroll") for (int k = 0; k < 2; ++k) \
;         acc[ai][bj][m][n] = __builtin_amdgcn_mfma_f32_16x16x32_bf16(Bt[n][k], At[m][k], acc[ai][bj][m][n], 0, 0, 0); __builtin_amdgcn_s_setprio(0); } while (0)
; #define PG8_WAIT_V(n) asm volatile("s_waitcnt vmcnt(" #n ")" ::: "memory")
; #define PG8_WAIT_L(n) asm volatile("s_waitcnt lgkmcnt(" #n ")" ::: "memory")
; #define PG8_BAR __builtin_amdgcn_s_barrier()
; #define PG8_SCHED __builtin_amdgcn_sched_barrier(0)
; template <class Epi, class Sched, bool ALIGN_EPI = false, bool SP2 = false>
; __device__ __forceinline__ void gemm_phase(PG8_LAS unsigned char* lds, const Gemm g, const Sched& S, const Epi& E) {
;     ...
;             PG8_LDA(At, 1, 1); PG8_STAGE(PG8_SB(1, 0), b3, voffB); PG8_STAGE(PG8_SB(1, 1), b3 + hstep, voffB); PG8_STAGE(PG8_SA(1, 0), a3, voffA);
;             PG8_WAIT_V(8); PG8_WAIT_L(0); PG8_BAR; PG8_MMA(1, 0, At, B0); PG8_MMA(1, 1, At, B1); PG8_BAR; PG8_SCHED;
;     ...
;         if constexpr (ALIGN_EPI) { if (wr == 0) PG8_BAR; }
	s_add_i32 s10, s10, s56
	v_lshl_add_u64 v[200:201], v[200:201], 0, s[30:31]
	s_mov_b32 m0, s10
	ds_read_b128 v[188:191], v159 offset:49152
	ds_read_b128 v[192:195], v159 offset:50176
	ds_read_b128 v[196:199], v159 offset:51200
	ds_read_b128 v[216:219], v159 offset:52224
	ds_read_b128 v[220:223], v159 offset:53248
	ds_read_b128 v[224:227], v159 offset:54272
	ds_read_b128 v[228:231], v159 offset:55296
	ds_read_b128 v[232:235], v159 offset:56320
	global_load_lds_dwordx4 v[200:201], off
	s_add_i32 m0, s10, 0x2000
	s_add_u32 s18, s18, 0x80080
	v_lshl_add_u64 v[200:201], v[236:237], 0, s[30:31]
	s_addc_u32 s19, s19, 0
	s_add_i32 s10, s11, s56
	global_load_lds_dwordx4 v[200:201], off
	v_lshl_add_u64 v[200:201], s[18:19], 0, v[0:1]
	s_mov_b32 m0, s10
	s_nop 0
	global_load_lds_dwordx4 v[200:201], off
	v_lshl_add_u64 v[200:201], s[18:19], 0, v[142:143]
	s_add_i32 m0, s10, 0x2000
	s_nop 0
	global_load_lds_dwordx4 v[200:201], off
	v_lshl_add_u64 v[200:201], v[238:239], 0, s[30:31]
	s_mov_b32 m0, s61
	s_nop 0
	global_load_lds_dwordx4 v[200:201], off
	v_lshl_add_u64 v[200:201], v[240:241], 0, s[30:31]
	s_mov_b32 m0, s62
	s_nop 0
	global_load_lds_dwordx4 v[200:201], off
	s_waitcnt vmcnt(8)
	s_waitcnt lgkmcnt(0)
	s_barrier
	v_mfma_f32_16x16x32_bf16 v[62:65], v[152:155], v[188:191], v[62:65]
	v_mfma_f32_16x16x32_bf16 v[58:61], v[164:167], v[188:191], v[58:61]
	v_mfma_f32_16x16x32_bf16 v[50:53], v[152:155], v[196:199], v[50:53]
	v_mfma_f32_16x16x32_bf16 v[42:45], v[164:167], v[196:199], v[42:45]
	v_mfma_f32_16x16x32_bf16 v[34:37], v[152:155], v[220:223], v[34:37]
	v_mfma_f32_16x16x32_bf16 v[26:29], v[164:167], v[220:223], v[26:29]
	v_mfma_f32_16x16x32_bf16 v[18:21], v[152:155], v[228:231], v[18:21]
	v_mfma_f32_16x16x32_bf16 v[10:13], v[164:167], v[228:231], v[10:13]
	v_mfma_f32_16x16x32_bf16 v[62:65], v[160:163], v[192:195], v[62:65]
	v_mfma_f32_16x16x32_bf16 v[58:61], v[168:171], v[192:195], v[58:61]
	v_mfma_f32_16x16x32_bf16 v[50:53], v[160:163], v[216:219], v[50:53]
	v_mfma_f32_16x16x32_bf16 v[42:45], v[168:171], v[216:219], v[42:45]
	v_mfma_f32_16x16x32_bf16 v[34:37], v[160:163], v[224:227], v[34:37]
	v_mfma_f32_16x16x32_bf16 v[26:29], v[168:171], v[224:227], v[26:29]
	v_mfma_f32_16x16x32_bf16 v[18:21], v[160:163], v[232:235], v[18:21]
	v_mfma_f32_16x16x32_bf16 v[10:13], v[168:171], v[232:235], v[10:13]
	v_mfma_f32_16x16x32_bf16 v[54:57], v[172:175], v[188:191], v[54:57]
	v_mfma_f32_16x16x32_bf16 v[46:49], v[180:183], v[188:191], v[46:49]
	v_mfma_f32_16x16x32_bf16 v[38:41], v[172:175], v[196:199], v[38:41]
	v_mfma_f32_16x16x32_bf16 v[30:33], v[180:183], v[196:199], v[30:33]
	v_mfma_f32_16x16x32_bf16 v[22:25], v[172:175], v[220:223], v[22:25]
	v_mfma_f32_16x16x32_bf16 v[14:17], v[180:183], v[220:223], v[14:17]
	v_mfma_f32_16x16x32_bf16 v[6:9], v[172:175], v[228:231], v[6:9]
	v_mfma_f32_16x16x32_bf16 v[2:5], v[180:183], v[228:231], v[2:5]
	v_mfma_f32_16x16x32_bf16 v[54:57], v[176:179], v[192:195], v[54:57]
	v_mfma_f32_16x16x32_bf16 v[46:49], v[184:187], v[192:195], v[46:49]
	v_mfma_f32_16x16x32_bf16 v[38:41], v[176:179], v[216:219], v[38:41]
	v_mfma_f32_16x16x32_bf16 v[30:33], v[184:187], v[216:219], v[30:33]
	v_mfma_f32_16x16x32_bf16 v[22:25], v[176:179], v[224:227], v[22:25]
	v_mfma_f32_16x16x32_bf16 v[14:17], v[184:187], v[224:227], v[14:17]
	v_mfma_f32_16x16x32_bf16 v[6:9], v[176:179], v[232:235], v[6:9]
	v_mfma_f32_16x16x32_bf16 v[2:5], v[184:187], v[232:235], v[2:5]
	s_barrier
	s_add_i32 s23, s23, 2
	s_add_u32 s16, s16, 0x100
	s_addc_u32 s17, s17, 0
	s_add_u32 s15, s15, 0x100
	s_addc_u32 s22, s22, 0
	s_cmp_gt_u32 s23, 29
	s_cbranch_scc0 .LBB0_265
	s_and_b64 vcc, exec, s[24:25]
	s_cbranch_vccz .LBB0_268
	s_barrier

; #define PG8_STAGE(bufoff, gbase, voff) do { _Pragma("unroll") for (int _i = 0; _i < 2; ++_i) \
;         __builtin_amdgcn_global_load_lds((const unsigned*)((const char*)(gbase) + (voff)[_i]), (PG8_LAS unsigned*)(lds + (bufoff) + ldsw + _i * 8192), 16, 0, 0); } while (0)
; #define PG8_LDA(dst, b, h) do { _Pragma("unroll") for (int m = 0; m < 4; ++m) _Pragma("unroll") for (int k = 0; k < 2; ++k) dst[m][k] = *(const PG8_LAS bf16x8*)(lds + PG8_SA(b, h) + aoff + m * 2048 + k * 1024); } while (0)
; #define PG8_LDB(dst, b, h) do { _Pragma("unroll") for (int n = 0; n < 2; ++n) _Pragma("unroll") for (int k = 0; k < 2; ++k) dst[n][k] = *(const PG8_LAS bf16x8*)(lds + PG8_SB(b, h) + boff + n * 2048 + k * 1024); } while (0)
; #define PG8_MMA(ai, bj, At, Bt) do { __builtin_amdgcn_s_setprio(1); _Pragma("unroll") for (int m = 0; m < 4; ++m) _Pragma("unroll") for (int n = 0; n < 2; ++n) _Pragma("unroll") for (int k = 0; k < 2; ++k) \
;         acc[ai][bj][m][n] = __builtin_amdgcn_mfma_f32_16x16x32_bf16(Bt[n][k], At[m][k], acc[ai][bj][m][n], 0, 0, 0); __builtin_amdgcn_s_setprio(0); } while (0)
; #define PG8_WAIT_V(n) asm volatile("s_waitcnt vmcnt(" #n ")" ::: "memory")
; #define PG8_WAIT_L(n) asm volatile("s_waitcnt lgkmcnt(" #n ")" ::: "memory")
; template <class Epi, class Sched, bool ALIGN_EPI = false, bool SP2 = false>
; __device__ __forceinline__ void gemm_phase(PG8_LAS unsigned char* lds, const Gemm g, const Sched& S, const Epi& E) {
;     ...
;             const bool last = (t == nt - 2);
;             const char* a1 = cA + (size_t)(t + 1) * kstep;
;             const char* a2 = last ? nA : cA + (size_t)(t + 2) * kstep; const char* b2 = last ? nB : cB + (size_t)(t + 2) * kstep;
;             const char* a3 = a2 + kstep; const char* b3 = b2 + kstep;
;             if (last && has_next) S.a_ready(nxt);
;             if constexpr (SP2) {
;             PG8_LDB(B0, 0, 0); PG8_LDB(B1, 0, 1); PG8_SCHED; PG8_LDA(At, 0, 0); PG8_STAGE(PG8_SA(1, 1), a1 + hstep, voffA);
;             PG8_WAIT_V(8); PG8_WAIT_L(0); PG8_BAR; PG8_MMA(0, 0, At, B0); PG8_MMA(0, 1, At, B1); PG8_BAR; PG8_SCHED;
;             PG8_LDA(At, 0, 1); PG8_STAGE(PG8_SB(0, 0), b2, voffB); PG8_STAGE(PG8_SB(0, 1), b2 + hstep, voffB); PG8_STAGE(PG8_SA(0, 0), a2, voffA);
;             PG8_WAIT_V(8); PG8_WAIT_L(0); PG8_BAR; PG8_MMA(1, 0, At, B0); PG8_MMA(1, 1, At, B1); PG8_BAR; PG8_SCHED;
.LBB0_601:
	s_add_u32 s18, s16, 0x100
	s_addc_u32 s19, s17, 0
	s_add_i32 s10, 0, 0x10000
	s_cmp_eq_u32 s22, 28
	s_cselect_b32 s27, s5, s19
	s_cselect_b32 s26, s7, s18
	s_cselect_b32 s25, s8, s15
	s_cselect_b32 s24, s9, s14
	s_add_i32 s12, 0, 0x14000
	v_add_u32_e32 v160, s10, v187
	v_add_u32_e32 v176, s12, v187
	ds_read_b128 v[148:151], v160
	ds_read_b128 v[152:155], v160 offset:1024
	ds_read_b128 v[156:159], v160 offset:2048
	ds_read_b128 v[160:163], v160 offset:3072
	ds_read_b128 v[164:167], v176
	ds_read_b128 v[168:171], v176 offset:1024
	ds_read_b128 v[172:175], v176 offset:2048
	ds_read_b128 v[176:179], v176 offset:3072
	v_lshl_add_u64 v[184:185], s[16:17], 0, v[144:145]
	s_add_i32 m0, s61, 0xc000
	ds_read_b128 v[180:183], v189
	ds_read_b128 v[190:193], v189 offset:1024
	ds_read_b128 v[194:197], v189 offset:2048
	ds_read_b128 v[198:201], v189 offset:3072
	ds_read_b128 v[216:219], v189 offset:4096
	ds_read_b128 v[220:223], v189 offset:5120
	ds_read_b128 v[224:227], v189 offset:6144
	ds_read_b128 v[228:231], v189 offset:7168
	global_load_lds_dwordx4 v[184:185], off
	v_lshl_add_u64 v[184:185], s[16:17], 0, v[146:147]
	s_add_i32 m0, s61, 0xe000
	s_nop 0
	global_load_lds_dwordx4 v[184:185], off
	s_waitcnt vmcnt(8)
	s_waitcnt lgkmcnt(0)
	s_barrier
	v_mfma_f32_16x16x32_bf16 v[126:129], v[148:151], v[180:183], v[126:129]
	v_mfma_f32_16x16x32_bf16 v[122:125], v[156:159], v[180:183], v[122:125]
	v_mfma_f32_16x16x32_bf16 v[110:113], v[148:151], v[194:197], v[110:113]
	v_mfma_f32_16x16x32_bf16 v[106:109], v[156:159], v[194:197], v[106:109]
	v_mfma_f32_16x16x32_bf16 v[94:97], v[148:151], v[216:219], v[94:97]
	v_mfma_f32_16x16x32_bf16 v[90:93], v[156:159], v[216:219], v[90:93]
	v_mfma_f32_16x16x32_bf16 v[78:81], v[148:151], v[224:227], v[78:81]
	v_mfma_f32_16x16x32_bf16 v[74:77], v[156:159], v[224:227], v[74:77]
	v_mfma_f32_16x16x32_bf16 v[126:129], v[152:155], v[190:193], v[126:129]
	v_mfma_f32_16x16x32_bf16 v[122:125], v[160:163], v[190:193], v[122:125]
	v_mfma_f32_16x16x32_bf16 v[110:113], v[152:155], v[198:201], v[110:113]
	v_mfma_f32_16x16x32_bf16 v[106:109], v[160:163], v[198:201], v[106:109]
	v_mfma_f32_16x16x32_bf16 v[94:97], v[152:155], v[220:223], v[94:97]
	v_mfma_f32_16x16x32_bf16 v[90:93], v[160:163], v[220:223], v[90:93]
	v_mfma_f32_16x16x32_bf16 v[78:81], v[152:155], v[228:231], v[78:81]
	v_mfma_f32_16x16x32_bf16 v[74:77], v[160:163], v[228:231], v[74:77]
	v_mfma_f32_16x16x32_bf16 v[118:121], v[164:167], v[180:183], v[118:121]
	v_mfma_f32_16x16x32_bf16 v[114:117], v[172:175], v[180:183], v[114:117]
	v_mfma_f32_16x16x32_bf16 v[102:105], v[164:167], v[194:197], v[102:105]
	v_mfma_f32_16x16x32_bf16 v[98:101], v[172:175], v[194:197], v[98:101]
	v_mfma_f32_16x16x32_bf16 v[86:89], v[164:167], v[216:219], v[86:89]
	v_mfma_f32_16x16x32_bf16 v[82:85], v[172:175], v[216:219], v[82:85]
	v_mfma_f32_16x16x32_bf16 v[70:73], v[164:167], v[224:227], v[70:73]
	v_mfma_f32_16x16x32_bf16 v[66:69], v[172:175], v[224:227], v[66:69]
	v_mfma_f32_16x16x32_bf16 v[118:121], v[168:171], v[190:193], v[118:121]
	v_mfma_f32_16x16x32_bf16 v[114:117], v[176:179], v[190:193], v[114:117]
	v_mfma_f32_16x16x32_bf16 v[102:105], v[168:171], v[198:201], v[102:105]
	v_mfma_f32_16x16x32_bf16 v[98:101], v[176:179], v[198:201], v[98:101]
	v_mfma_f32_16x16x32_bf16 v[86:89], v[168:171], v[220:223], v[86:89]
	v_mfma_f32_16x16x32_bf16 v[82:85], v[176:179], v[220:223], v[82:85]
	v_mfma_f32_16x16x32_bf16 v[70:73], v[168:171], v[228:231], v[70:73]
	v_mfma_f32_16x16x32_bf16 v[66:69], v[176:179], v[228:231], v[66:69]
	s_barrier
	s_add_i32 s10, s10, s60
	v_lshl_add_u64 v[184:185], s[24:25], 0, v[0:1]
	s_mov_b32 m0, s10
	ds_read_b128 v[180:183], v189 offset:16384
	ds_read_b128 v[190:193], v189 offset:17408
	ds_read_b128 v[194:197], v189 offset:18432
	ds_read_b128 v[198:201], v189 offset:19456
	ds_read_b128 v[216:219], v189 offset:20480
	ds_read_b128 v[220:223], v189 offset:21504
	ds_read_b128 v[224:227], v189 offset:22528
	ds_read_b128 v[228:231], v189 offset:23552
	global_load_lds_dwordx4 v[184:185], off
	s_add_i32 m0, s10, 0x2000
	s_add_u32 s10, s24, 0x80000
	v_lshl_add_u64 v[232:233], s[24:25], 0, v[142:143]
	s_addc_u32 s11, s25, 0
	s_add_i32 s12, s12, s60
	global_load_lds_dwordx4 v[232:233], off
	v_lshl_add_u64 v[234:235], s[10:11], 0, v[0:1]
	s_mov_b32 m0, s12
	v_lshl_add_u64 v[236:237], s[26:27], 0, v[142:143]
	global_load_lds_dwordx4 v[234:235], off
	v_lshl_add_u64 v[234:235], s[10:11], 0, v[142:143]
	s_add_i32 m0, s12, 0x2000
	s_nop 0
	global_load_lds_dwordx4 v[234:235], off
	v_lshl_add_u64 v[234:235], s[26:27], 0, v[0:1]
	s_mov_b32 m0, s61
	s_nop 0
	global_load_lds_dwordx4 v[234:235], off
	s_mov_b32 m0, s62
	s_nop 0
	global_load_lds_dwordx4 v[236:237], off
	s_waitcnt vmcnt(8)
	s_waitcnt lgkmcnt(0)
	s_barrier
; #define PG8_STAGE(bufoff, gbase, voff) do { _Pragma("unroll") for (int _i = 0; _i < 2; ++_i) \
;         __builtin_amdgcn_global_load_lds((const unsigned*)((const char*)(gbase) + (voff)[_i]), (PG8_LAS unsigned*)(lds + (bufoff) + ldsw + _i * 8192), 16, 0, 0); } while (0)
; #define PG8_LDA(dst, b, h) do { _Pragma("unroll") for (int m = 0; m < 4; ++m) _Pragma("unroll") for (int k = 0; k < 2; ++k) dst[m][k] = *(const PG8_LAS bf16x8*)(lds + PG8_SA(b, h) + aoff + m * 2048 + k * 1024); } while (0)
; #define PG8_LDB(dst, b, h) do { _Pragma("unroll") for (int n = 0; n < 2; ++n) _Pragma("unroll") for (int k = 0; k < 2; ++k) dst[n][k] = *(const PG8_LAS bf16x8*)(lds + PG8_SB(b, h) + boff + n * 2048 + k * 1024); } while (0)
; #define PG8_MMA(ai, bj, At, Bt) do { __builtin_amdgcn_s_setprio(1); _Pragma("unroll") for (int m = 0; m < 4; ++m) _Pragma("unroll") for (int n = 0; n < 2; ++n) _Pragma("unroll") for (int k = 0; k < 2; ++k) \
;         acc[ai][bj][m][n] = __builtin_amdgcn_mfma_f32_16x16x32_bf16(Bt[n][k], At[m][k], acc[ai][bj][m][n], 0, 0, 0); __builtin_amdgcn_s_setprio(0); } while (0)
; #define PG8_WAIT_V(n) asm volatile("s_waitcnt vmcnt(" #n ")" ::: "memory")
; #define PG8_WAIT_L(n) asm volatile("s_waitcnt lgkmcnt(" #n ")" ::: "memory")
; #define PG8_BAR __builtin_amdgcn_s_barrier()
; #define PG8_SCHED __builtin_amdgcn_sched_barrier(0)
; template <class Epi, class Sched, bool ALIGN_EPI = false, bool SP2 = false>
; __device__ __forceinline__ void gemm_phase(PG8_LAS unsigned char* lds, const Gemm g, const Sched& S, const Epi& E) {
;     ...
;             PG8_WAIT_V(8); PG8_WAIT_L(0); PG8_BAR; PG8_MMA(1, 0, At, B0); PG8_MMA(1, 1, At, B1); PG8_BAR; PG8_SCHED;
;             PG8_LDB(B0, 1, 0); PG8_LDB(B1, 1, 1); PG8_SCHED; PG8_LDA(At, 1, 0); PG8_STAGE(PG8_SA(0, 1), a2 + hstep, voffA);
;             PG8_WAIT_V(8); PG8_WAIT_L(0); PG8_BAR; PG8_MMA(0, 0, At, B0); PG8_MMA(0, 1, At, B1); PG8_BAR; PG8_SCHED;
	v_mfma_f32_16x16x32_bf16 v[62:65], v[148:151], v[180:183], v[62:65]
	v_mfma_f32_16x16x32_bf16 v[58:61], v[156:159], v[180:183], v[58:61]
	v_mfma_f32_16x16x32_bf16 v[46:49], v[148:151], v[194:197], v[46:49]
	v_mfma_f32_16x16x32_bf16 v[42:45], v[156:159], v[194:197], v[42:45]
	v_mfma_f32_16x16x32_bf16 v[30:33], v[148:151], v[216:219], v[30:33]
	v_mfma_f32_16x16x32_bf16 v[26:29], v[156:159], v[216:219], v[26:29]
	v_mfma_f32_16x16x32_bf16 v[14:17], v[148:151], v[224:227], v[14:17]
	v_mfma_f32_16x16x32_bf16 v[10:13], v[156:159], v[224:227], v[10:13]
	v_mfma_f32_16x16x32_bf16 v[62:65], v[152:155], v[190:193], v[62:65]
	v_mfma_f32_16x16x32_bf16 v[58:61], v[160:163], v[190:193], v[58:61]
	v_mfma_f32_16x16x32_bf16 v[46:49], v[152:155], v[198:201], v[46:49]
	v_mfma_f32_16x16x32_bf16 v[42:45], v[160:163], v[198:201], v[42:45]
	v_mfma_f32_16x16x32_bf16 v[30:33], v[152:155], v[220:223], v[30:33]
	v_mfma_f32_16x16x32_bf16 v[26:29], v[160:163], v[220:223], v[26:29]
	v_mfma_f32_16x16x32_bf16 v[14:17], v[152:155], v[228:231], v[14:17]
	v_mfma_f32_16x16x32_bf16 v[10:13], v[160:163], v[228:231], v[10:13]
	v_mfma_f32_16x16x32_bf16 v[54:57], v[164:167], v[180:183], v[54:57]
	v_mfma_f32_16x16x32_bf16 v[50:53], v[172:175], v[180:183], v[50:53]
	v_mfma_f32_16x16x32_bf16 v[38:41], v[164:167], v[194:197], v[38:41]
	v_mfma_f32_16x16x32_bf16 v[34:37], v[172:175], v[194:197], v[34:37]
	v_mfma_f32_16x16x32_bf16 v[22:25], v[164:167], v[216:219], v[22:25]
	v_mfma_f32_16x16x32_bf16 v[18:21], v[172:175], v[216:219], v[18:21]
	v_mfma_f32_16x16x32_bf16 v[6:9], v[164:167], v[224:227], v[6:9]
	v_mfma_f32_16x16x32_bf16 v[2:5], v[172:175], v[224:227], v[2:5]
	v_mfma_f32_16x16x32_bf16 v[54:57], v[168:171], v[190:193], v[54:57]
	v_mfma_f32_16x16x32_bf16 v[50:53], v[176:179], v[190:193], v[50:53]
	v_mfma_f32_16x16x32_bf16 v[38:41], v[168:171], v[198:201], v[38:41]
	v_mfma_f32_16x16x32_bf16 v[34:37], v[176:179], v[198:201], v[34:37]
	v_mfma_f32_16x16x32_bf16 v[22:25], v[168:171], v[220:223], v[22:25]
	v_mfma_f32_16x16x32_bf16 v[18:21], v[176:179], v[220:223], v[18:21]
	v_mfma_f32_16x16x32_bf16 v[6:9], v[168:171], v[228:231], v[6:9]
	v_mfma_f32_16x16x32_bf16 v[2:5], v[176:179], v[228:231], v[2:5]
	s_barrier
	s_add_i32 s12, 0, 0x18000
	s_add_i32 s13, 0, 0x1c000
	v_add_u32_e32 v160, s12, v187
	v_add_u32_e32 v176, s13, v187
	ds_read_b128 v[148:151], v160
	ds_read_b128 v[152:155], v160 offset:1024
	ds_read_b128 v[156:159], v160 offset:2048
	ds_read_b128 v[160:163], v160 offset:3072
	ds_read_b128 v[164:167], v176
	ds_read_b128 v[168:171], v176 offset:1024
	ds_read_b128 v[172:175], v176 offset:2048
	ds_read_b128 v[176:179], v176 offset:3072
	s_add_u32 s10, s26, 0x80000
	s_addc_u32 s11, s27, 0
	s_mov_b32 m0, s63
	v_lshl_add_u64 v[238:239], s[10:11], 0, v[0:1]
	ds_read_b128 v[180:183], v189 offset:32768
	ds_read_b128 v[190:193], v189 offset:33792
	ds_read_b128 v[194:197], v189 offset:34816
	ds_read_b128 v[198:201], v189 offset:35840
	ds_read_b128 v[216:219], v189 offset:36864
	ds_read_b128 v[220:223], v189 offset:37888
	ds_read_b128 v[224:227], v189 offset:38912
	ds_read_b128 v[228:231], v189 offset:39936
	global_load_lds_dwordx4 v[238:239], off
	v_lshl_add_u64 v[238:239], s[10:11], 0, v[142:143]
	s_mov_b32 m0, s64
	s_nop 0
	global_load_lds_dwordx4 v[238:239], off
	s_waitcnt vmcnt(8)
	s_waitcnt lgkmcnt(0)
	s_barrier
	v_mfma_f32_16x16x32_bf16 v[126:129], v[148:151], v[180:183], v[126:129]
	v_mfma_f32_16x16x32_bf16 v[122:125], v[156:159], v[180:183], v[122:125]
	v_mfma_f32_16x16x32_bf16 v[110:113], v[148:151], v[194:197], v[110:113]
	v_mfma_f32_16x16x32_bf16 v[106:109], v[156:159], v[194:197], v[106:109]
	v_mfma_f32_16x16x32_bf16 v[94:97], v[148:151], v[216:219], v[94:97]
	v_mfma_f32_16x16x32_bf16 v[90:93], v[156:159], v[216:219], v[90:93]
	v_mfma_f32_16x16x32_bf16 v[78:81], v[148:151], v[224:227], v[78:81]
	v_mfma_f32_16x16x32_bf16 v[74:77], v[156:159], v[224:227], v[74:77]
	v_mfma_f32_16x16x32_bf16 v[126:129], v[152:155], v[190:193], v[126:129]
	v_mfma_f32_16x16x32_bf16 v[122:125], v[160:163], v[190:193], v[122:125]
	v_mfma_f32_16x16x32_bf16 v[110:113], v[152:155], v[198:201], v[110:113]
	v_mfma_f32_16x16x32_bf16 v[106:109], v[160:163], v[198:201], v[106:109]
	v_mfma_f32_16x16x32_bf16 v[94:97], v[152:155], v[220:223], v[94:97]
	v_mfma_f32_16x16x32_bf16 v[90:93], v[160:163], v[220:223], v[90:93]
	v_mfma_f32_16x16x32_bf16 v[78:81], v[152:155], v[228:231], v[78:81]
	v_mfma_f32_16x16x32_bf16 v[74:77], v[160:163], v[228:231], v[74:77]
	v_mfma_f32_16x16x32_bf16 v[118:121], v[164:167], v[180:183], v[118:121]
	v_mfma_f32_16x16x32_bf16 v[114:117], v[172:175], v[180:183], v[114:117]
	v_mfma_f32_16x16x32_bf16 v[102:105], v[164:167], v[194:197], v[102:105]
	v_mfma_f32_16x16x32_bf16 v[98:101], v[172:175], v[194:197], v[98:101]
	v_mfma_f32_16x16x32_bf16 v[86:89], v[164:167], v[216:219], v[86:89]
	v_mfma_f32_16x16x32_bf16 v[82:85], v[172:175], v[216:219], v[82:85]
	v_mfma_f32_16x16x32_bf16 v[70:73], v[164:167], v[224:227], v[70:73]
	v_mfma_f32_16x16x32_bf16 v[66:69], v[172:175], v[224:227], v[66:69]
	v_mfma_f32_16x16x32_bf16 v[118:121], v[168:171], v[190:193], v[118:121]
	v_mfma_f32_16x16x32_bf16 v[114:117], v[176:179], v[190:193], v[114:117]
	v_mfma_f32_16x16x32_bf16 v[102:105], v[168:171], v[198:201], v[102:105]
	v_mfma_f32_16x16x32_bf16 v[98:101], v[176:179], v[198:201], v[98:101]
	v_mfma_f32_16x16x32_bf16 v[86:89], v[168:171], v[220:223], v[86:89]
	v_mfma_f32_16x16x32_bf16 v[82:85], v[176:179], v[220:223], v[82:85]
	v_mfma_f32_16x16x32_bf16 v[70:73], v[168:171], v[228:231], v[70:73]
	v_mfma_f32_16x16x32_bf16 v[66:69], v[176:179], v[228:231], v[66:69]
	s_barrier
; #define PG8_STAGE(bufoff, gbase, voff) do { _Pragma("unroll") for (int _i = 0; _i < 2; ++_i) \
;         __builtin_amdgcn_global_load_lds((const unsigned*)((const char*)(gbase) + (voff)[_i]), (PG8_LAS unsigned*)(lds + (bufoff) + ldsw + _i * 8192), 16, 0, 0); } while (0)
; #define PG8_LDA(dst, b, h) do { _Pragma("unroll") for (int m = 0; m < 4; ++m) _Pragma("unroll") for (int k = 0; k < 2; ++k) dst[m][k] = *(const PG8_LAS bf16x8*)(lds + PG8_SA(b, h) + aoff + m * 2048 + k * 1024); } while (0)
; #define PG8_MMA(ai, bj, At, Bt) do { __builtin_amdgcn_s_setprio(1); _Pragma("unroll") for (int m = 0; m < 4; ++m) _Pragma("unroll") for (int n = 0; n < 2; ++n) _Pragma("unroll") for (int k = 0; k < 2; ++k) \
;         acc[ai][bj][m][n] = __builtin_amdgcn_mfma_f32_16x16x32_bf16(Bt[n][k], At[m][k], acc[ai][bj][m][n], 0, 0, 0); __builtin_amdgcn_s_setprio(0); } while (0)
; #define PG8_WAIT_V(n) asm volatile("s_waitcnt vmcnt(" #n ")" ::: "memory")
; #define PG8_WAIT_L(n) asm volatile("s_waitcnt lgkmcnt(" #n ")" ::: "memory")
; #define PG8_BAR __builtin_amdgcn_s_barrier()
; #define PG8_SCHED __builtin_amdgcn_sched_barrier(0)
; template <class Epi, class Sched, bool ALIGN_EPI = false, bool SP2 = false>
; __device__ __forceinline__ void gemm_phase(PG8_LAS unsigned char* lds, const Gemm g, const Sched& S, const Epi& E) {
;     ...
;             PG8_LDA(At, 1, 1); PG8_STAGE(PG8_SB(1, 0), b3, voffB); PG8_STAGE(PG8_SB(1, 1), b3 + hstep, voffB); PG8_STAGE(PG8_SA(1, 0), a3, voffA);
;             PG8_WAIT_V(8); PG8_WAIT_L(0); PG8_BAR; PG8_MMA(1, 0, At, B0); PG8_MMA(1, 1, At, B1); PG8_BAR; PG8_SCHED;
	s_add_i32 s10, s12, s60
	v_lshl_add_u64 v[184:185], v[184:185], 0, s[30:31]
	s_mov_b32 m0, s10
	ds_read_b128 v[180:183], v189 offset:49152
	ds_read_b128 v[190:193], v189 offset:50176
	ds_read_b128 v[194:197], v189 offset:51200
	ds_read_b128 v[198:201], v189 offset:52224
	ds_read_b128 v[216:219], v189 offset:53248
	ds_read_b128 v[220:223], v189 offset:54272
	ds_read_b128 v[224:227], v189 offset:55296
	ds_read_b128 v[228:231], v189 offset:56320
	global_load_lds_dwordx4 v[184:185], off
	s_add_i32 m0, s10, 0x2000
	s_add_u32 s10, s24, 0x80080
	v_lshl_add_u64 v[184:185], v[232:233], 0, s[30:31]
	s_addc_u32 s11, s25, 0
	s_add_i32 s12, s13, s60
	global_load_lds_dwordx4 v[184:185], off
	v_lshl_add_u64 v[184:185], s[10:11], 0, v[0:1]
	s_mov_b32 m0, s12
	s_nop 0
	global_load_lds_dwordx4 v[184:185], off
	v_lshl_add_u64 v[184:185], s[10:11], 0, v[142:143]
	s_add_i32 m0, s12, 0x2000
	s_nop 0
	global_load_lds_dwordx4 v[184:185], off
	v_lshl_add_u64 v[184:185], v[234:235], 0, s[30:31]
	s_mov_b32 m0, s65
	s_nop 0
	global_load_lds_dwordx4 v[184:185], off
	v_lshl_add_u64 v[184:185], v[236:237], 0, s[30:31]
	s_mov_b32 m0, s66
	s_nop 0
	global_load_lds_dwordx4 v[184:185], off
	s_waitcnt vmcnt(8)
	s_waitcnt lgkmcnt(0)
	s_barrier
	v_mfma_f32_16x16x32_bf16 v[62:65], v[148:151], v[180:183], v[62:65]
	v_mfma_f32_16x16x32_bf16 v[58:61], v[156:159], v[180:183], v[58:61]
	v_mfma_f32_16x16x32_bf16 v[46:49], v[148:151], v[194:197], v[46:49]
	v_mfma_f32_16x16x32_bf16 v[42:45], v[156:159], v[194:197], v[42:45]
	v_mfma_f32_16x16x32_bf16 v[30:33], v[148:151], v[216:219], v[30:33]
	v_mfma_f32_16x16x32_bf16 v[26:29], v[156:159], v[216:219], v[26:29]
	v_mfma_f32_16x16x32_bf16 v[14:17], v[148:151], v[224:227], v[14:17]
	v_mfma_f32_16x16x32_bf16 v[10:13], v[156:159], v[224:227], v[10:13]
	v_mfma_f32_16x16x32_bf16 v[62:65], v[152:155], v[190:193], v[62:65]
	v_mfma_f32_16x16x32_bf16 v[58:61], v[160:163], v[190:193], v[58:61]
	v_mfma_f32_16x16x32_bf16 v[46:49], v[152:155], v[198:201], v[46:49]
	v_mfma_f32_16x16x32_bf16 v[42:45], v[160:163], v[198:201], v[42:45]
	v_mfma_f32_16x16x32_bf16 v[30:33], v[152:155], v[220:223], v[30:33]
	v_mfma_f32_16x16x32_bf16 v[26:29], v[160:163], v[220:223], v[26:29]
	v_mfma_f32_16x16x32_bf16 v[14:17], v[152:155], v[228:231], v[14:17]
	v_mfma_f32_16x16x32_bf16 v[10:13], v[160:163], v[228:231], v[10:13]
	v_mfma_f32_16x16x32_bf16 v[54:57], v[164:167], v[180:183], v[54:57]
	v_mfma_f32_16x16x32_bf16 v[50:53], v[172:175], v[180:183], v[50:53]
	v_mfma_f32_16x16x32_bf16 v[38:41], v[164:167], v[194:197], v[38:41]
	v_mfma_f32_16x16x32_bf16 v[34:37], v[172:175], v[194:197], v[34:37]
	v_mfma_f32_16x16x32_bf16 v[22:25], v[164:167], v[216:219], v[22:25]
	v_mfma_f32_16x16x32_bf16 v[18:21], v[172:175], v[216:219], v[18:21]
	v_mfma_f32_16x16x32_bf16 v[6:9], v[164:167], v[224:227], v[6:9]
	v_mfma_f32_16x16x32_bf16 v[2:5], v[172:175], v[224:227], v[2:5]
	v_mfma_f32_16x16x32_bf16 v[54:57], v[168:171], v[190:193], v[54:57]
	v_mfma_f32_16x16x32_bf16 v[50:53], v[176:179], v[190:193], v[50:53]
	v_mfma_f32_16x16x32_bf16 v[38:41], v[168:171], v[198:201], v[38:41]
	v_mfma_f32_16x16x32_bf16 v[34:37], v[176:179], v[198:201], v[34:37]
	v_mfma_f32_16x16x32_bf16 v[22:25], v[168:171], v[220:223], v[22:25]
	v_mfma_f32_16x16x32_bf16 v[18:21], v[176:179], v[220:223], v[18:21]
	v_mfma_f32_16x16x32_bf16 v[6:9], v[168:171], v[228:231], v[6:9]
	v_mfma_f32_16x16x32_bf16 v[2:5], v[176:179], v[228:231], v[2:5]
	s_barrier
	s_add_i32 s22, s22, 2
	s_add_u32 s14, s14, 0x100
	s_addc_u32 s15, s15, 0
	s_cmp_gt_u32 s22, 29
	s_mov_b64 s[16:17], s[18:19]
	s_cbranch_scc0 .LBB0_601
; __device__ __forceinline__ unsigned cvt_pk_bf16(float lo, float hi) { unsigned r; asm volatile("v_cvt_pk_bf16_f32 %0, %1, %2" : "=v"(r) : "v"(lo), "v"(hi)); return r; }
;     __device__ __forceinline__ void operator()(const f32x4 (&acc)[2][2][4][2], const Unit& u, int wr, int wc, int fr, int fq) const {
;         const int row0 = u.pm * BM + wr * 64 + fr; const int col0 = u.pn * BM + wc * 32 + 4 * fq;
; #pragma unroll
;         for (int ai = 0; ai < 2; ++ai) {
;             u32x2 bv[4][2][2];
; #pragma unroll
;             for (int m = 0; m < 4; ++m) { const size_t off = (size_t)(row0 + ai * HALF + m * 16) * ldc + col0;
; #pragma unroll
;                 for (int bj = 0; bj < 2; ++bj)
; #pragma unroll
;                     for (int n = 0; n < 2; ++n) bv[m][bj][n] = *(const u32x2*)(xb + off + bj * HALF + n * 16); }
;             asm volatile("" ::: "memory");
; #pragma unroll
;             for (int m = 0; m < 4; ++m) {
;                 const int row = row0 + ai * HALF + m * 16;
;                 const size_t off = (size_t)row * ldc + col0;
;                 float s = 0.f;
; #pragma unroll
;                 for (int bj = 0; bj < 2; ++bj)
; #pragma unroll
;                     for (int n = 0; n < 2; ++n) {
;                         const size_t c = off + bj * HALF + n * 16;
;                         const u32x2 w0 = bv[m][bj][n];
;                         const f32x4 b = {__uint_as_float(w0.x << 16), __uint_as_float(w0.x & 0xffff0000u), __uint_as_float(w0.y << 16), __uint_as_float(w0.y & 0xffff0000u)};
;                         const f32x4 o = b + acc[ai][bj][m][n];
;                         if (fin) { *(f32x4*)(outf + c) = o; }
;                         else { u32x2 w; w.x = cvt_pk_bf16(o[0], o[1]); w.y = cvt_pk_bf16(o[2], o[3]); *(u32x2*)(xb + c) = w;
;                                s += (o[0] * o[0] + o[1] * o[1]) + (o[2] * o[2] + o[3] * o[3]); }
;                     }
;                 if (!fin) { s += __shfl_xor(s, 16); s += __shfl_xor(s, 32); if (fq == 0) unsafeAtomicAdd(ssq + row, s); }
	v_lshl_or_b32 v148, s2, 8, v188
	v_lshl_add_u32 v152, s4, 8, v186
	v_ashrrev_i32_e32 v149, 31, v148
	v_lshlrev_b64 v[190:191], 1, v[148:149]
	v_ashrrev_i32_e32 v153, 31, v152
	v_lshl_add_u64 v[150:151], s[48:49], 0, v[190:191]
	v_lshlrev_b64 v[154:155], 12, v[152:153]
	v_lshl_add_u64 v[156:157], v[150:151], 0, v[154:155]
	global_load_dwordx2 v[192:193], v[156:157], off
	global_load_dwordx2 v[194:195], v[156:157], off offset:32
	global_load_dwordx2 v[196:197], v[156:157], off offset:256
	global_load_dwordx2 v[198:199], v[156:157], off offset:288
	v_or_b32_e32 v184, 16, v152
	v_ashrrev_i32_e32 v185, 31, v184
	v_lshlrev_b64 v[156:157], 12, v[184:185]
	v_or_b32_e32 v174, 32, v152
	v_lshl_add_u64 v[156:157], v[150:151], 0, v[156:157]
	v_ashrrev_i32_e32 v175, 31, v174
	global_load_dwordx2 v[182:183], v[156:157], off
	global_load_dwordx2 v[180:181], v[156:157], off offset:32
	global_load_dwordx2 v[178:179], v[156:157], off offset:256
	global_load_dwordx2 v[176:177], v[156:157], off offset:288
	v_lshlrev_b64 v[156:157], 12, v[174:175]
	v_or_b32_e32 v158, 48, v152
	v_lshl_add_u64 v[156:157], v[150:151], 0, v[156:157]
	v_ashrrev_i32_e32 v159, 31, v158
	global_load_dwordx2 v[172:173], v[156:157], off
	global_load_dwordx2 v[170:171], v[156:157], off offset:32
	global_load_dwordx2 v[166:167], v[156:157], off offset:256
	global_load_dwordx2 v[162:163], v[156:157], off offset:288
	v_lshlrev_b64 v[156:157], 12, v[158:159]
	v_lshl_add_u64 v[156:157], v[150:151], 0, v[156:157]
	global_load_dwordx2 v[168:169], v[156:157], off
	global_load_dwordx2 v[164:165], v[156:157], off offset:32
	global_load_dwordx2 v[160:161], v[156:157], off offset:256
	s_nop 0
	global_load_dwordx2 v[156:157], v[156:157], off offset:288
	s_waitcnt vmcnt(0)
	v_lshlrev_b32_e32 v200, 16, v192
	v_and_b32_e32 v201, 0xffff0000, v192
	v_lshlrev_b32_e32 v192, 16, v193
	v_and_b32_e32 v193, 0xffff0000, v193
	v_pk_add_f32 v[126:127], v[126:127], v[200:201]
	v_pk_add_f32 v[128:129], v[128:129], v[192:193]
	v_cvt_pk_bf16_f32 v192, v126, v127
	v_mul_f32_e32 v127, v127, v127
	v_lshl_add_u64 v[200:201], s[48:49], 0, v[154:155]
	v_fmac_f32_e32 v127, v126, v126
	v_mul_f32_e32 v126, v129, v129
	v_lshl_add_u64 v[190:191], v[200:201], 0, v[190:191]
	v_fmac_f32_e32 v126, v128, v128
	v_cvt_pk_bf16_f32 v193, v128, v129
	global_store_dwordx2 v[190:191], v[192:193], off
	v_add_f32_e32 v192, v127, v126
	v_lshlrev_b32_e32 v126, 16, v194
	v_and_b32_e32 v127, 0xffff0000, v194
	v_lshlrev_b32_e32 v128, 16, v195
	v_and_b32_e32 v129, 0xffff0000, v195
	v_pk_add_f32 v[122:123], v[122:123], v[126:127]
	v_pk_add_f32 v[124:125], v[124:125], v[128:129]
	v_cvt_pk_bf16_f32 v126, v122, v123
	v_mul_f32_e32 v123, v123, v123
	v_fmac_f32_e32 v123, v122, v122
	v_mul_f32_e32 v122, v125, v125
	v_fmac_f32_e32 v122, v124, v124
	v_add_f32_e32 v122, v123, v122
	v_cvt_pk_bf16_f32 v127, v124, v125
	global_store_dwordx2 v[190:191], v[126:127], off offset:32
	v_add_f32_e32 v126, v192, v122
	v_lshlrev_b32_e32 v122, 16, v196
	v_and_b32_e32 v123, 0xffff0000, v196
	v_lshlrev_b32_e32 v124, 16, v197
	v_and_b32_e32 v125, 0xffff0000, v197
	v_pk_add_f32 v[118:119], v[118:119], v[122:123]
	v_pk_add_f32 v[120:121], v[120:121], v[124:125]
	v_cvt_pk_bf16_f32 v122, v118, v119
	v_mul_f32_e32 v119, v119, v119
	v_fmac_f32_e32 v119, v118, v118
	v_mul_f32_e32 v118, v121, v121
	v_fmac_f32_e32 v118, v120, v120
	v_add_f32_e32 v118, v119, v118
	v_cvt_pk_bf16_f32 v123, v120, v121
	global_store_dwordx2 v[190:191], v[122:123], off offset:256
	v_add_f32_e32 v122, v126, v118
	v_lshlrev_b32_e32 v118, 16, v198
	v_and_b32_e32 v119, 0xffff0000, v198
	v_lshlrev_b32_e32 v120, 16, v199
	v_and_b32_e32 v121, 0xffff0000, v199
	v_pk_add_f32 v[114:115], v[114:115], v[118:119]
	v_pk_add_f32 v[116:117], v[116:117], v[120:121]
	v_cvt_pk_bf16_f32 v118, v114, v115
	v_mul_f32_e32 v115, v115, v115
	v_fmac_f32_e32 v115, v114, v114
	v_mul_f32_e32 v114, v117, v117
	v_cvt_pk_bf16_f32 v119, v116, v117
	v_fmac_f32_e32 v114, v116, v116
	v_and_b32_e32 v116, 64, v208
	v_add_f32_e32 v114, v115, v114
	v_xor_b32_e32 v115, 16, v208
	v_add_u32_e32 v117, 64, v116
	v_cmp_lt_i32_e32 vcc, v115, v117
	v_add_f32_e32 v114, v122, v114
	global_store_dwordx2 v[190:191], v[118:119], off offset:288
	v_cndmask_b32_e32 v115, v208, v115, vcc
	v_lshlrev_b32_e32 v116, 2, v115
	ds_bpermute_b32 v115, v116, v114
	s_waitcnt lgkmcnt(0)
	v_add_f32_e32 v118, v114, v115
	v_xor_b32_e32 v114, 32, v208
	v_cmp_lt_i32_e32 vcc, v114, v117
	s_nop 1
	v_cndmask_b32_e32 v114, v208, v114, vcc
	v_lshlrev_b32_e32 v117, 2, v114
	ds_bpermute_b32 v119, v117, v118
	v_lshl_add_u64 v[114:115], v[152:153], 2, s[50:51]
	s_and_saveexec_b64 s[16:17], s[42:43]
	s_cbranch_execz .LBB0_604
	s_waitcnt lgkmcnt(0)
	v_add_f32_e32 v118, v118, v119
	global_atomic_add_f32 v[114:115], v118, off

; #define PG8_STAGE(bufoff, gbase, voff) do { _Pragma("unroll") for (int _i = 0; _i < 2; ++_i) \
;         __builtin_amdgcn_global_load_lds((const unsigned*)((const char*)(gbase) + (voff)[_i]), (PG8_LAS unsigned*)(lds + (bufoff) + ldsw + _i * 8192), 16, 0, 0); } while (0)
; #define PG8_LDA(dst, b, h) do { _Pragma("unroll") for (int m = 0; m < 4; ++m) _Pragma("unroll") for (int k = 0; k < 2; ++k) dst[m][k] = *(const PG8_LAS bf16x8*)(lds + PG8_SA(b, h) + aoff + m * 2048 + k * 1024); } while (0)
; #define PG8_LDB(dst, b, h) do { _Pragma("unroll") for (int n = 0; n < 2; ++n) _Pragma("unroll") for (int k = 0; k < 2; ++k) dst[n][k] = *(const PG8_LAS bf16x8*)(lds + PG8_SB(b, h) + boff + n * 2048 + k * 1024); } while (0)
; #define PG8_MMA(ai, bj, At, Bt) do { __builtin_amdgcn_s_setprio(1); _Pragma("unroll") for (int m = 0; m < 4; ++m) _Pragma("unroll") for (int n = 0; n < 2; ++n) _Pragma("unroll") for (int k = 0; k < 2; ++k) \
;         acc[ai][bj][m][n] = __builtin_amdgcn_mfma_f32_16x16x32_bf16(Bt[n][k], At[m][k], acc[ai][bj][m][n], 0, 0, 0); __builtin_amdgcn_s_setprio(0); } while (0)
; #define PG8_WAIT_V(n) asm volatile("s_waitcnt vmcnt(" #n ")" ::: "memory")
; #define PG8_WAIT_L(n) asm volatile("s_waitcnt lgkmcnt(" #n ")" ::: "memory")
; template <class Epi, class Sched, bool ALIGN_EPI = false, bool SP2 = false>
; __device__ __forceinline__ void gemm_phase(PG8_LAS unsigned char* lds, const Gemm g, const Sched& S, const Epi& E) {
;     ...
;             const bool last = (t == nt - 2);
;             const char* a1 = cA + (size_t)(t + 1) * kstep;
;             const char* a2 = last ? nA : cA + (size_t)(t + 2) * kstep; const char* b2 = last ? nB : cB + (size_t)(t + 2) * kstep;
;             const char* a3 = a2 + kstep; const char* b3 = b2 + kstep;
;             if (last && has_next) S.a_ready(nxt);
;             if constexpr (SP2) {
;             PG8_LDB(B0, 0, 0); PG8_LDB(B1, 0, 1); PG8_SCHED; PG8_LDA(At, 0, 0); PG8_STAGE(PG8_SA(1, 1), a1 + hstep, voffA);
;             PG8_WAIT_V(8); PG8_WAIT_L(0); PG8_BAR; PG8_MMA(0, 0, At, B0); PG8_MMA(0, 1, At, B1); PG8_BAR; PG8_SCHED;
;             PG8_LDA(At, 0, 1); PG8_STAGE(PG8_SB(0, 0), b2, voffB); PG8_STAGE(PG8_SB(0, 1), b2 + hstep, voffB); PG8_STAGE(PG8_SA(0, 0), a2, voffA);
;             PG8_WAIT_V(8); PG8_WAIT_L(0); PG8_BAR; PG8_MMA(1, 0, At, B0); PG8_MMA(1, 1, At, B1); PG8_BAR; PG8_SCHED;
.LBB0_686:
	s_add_u32 s10, s16, 0xfff80080
	s_addc_u32 s11, s17, -1
	s_add_i32 s12, 0, 0x10000
	s_cmp_eq_u32 s22, 28
	s_cselect_b32 s25, s5, s11
	s_cselect_b32 s24, s7, s10
	v_add_u32_e32 v160, s12, v163
	s_cselect_b32 s19, s8, s15
	s_cselect_b32 s18, s9, s14
	s_add_i32 s13, 0, 0x14000
	ds_read_b128 v[152:155], v160
	ds_read_b128 v[156:159], v160 offset:1024
	ds_read_b128 v[166:169], v160 offset:2048
	ds_read_b128 v[170:173], v160 offset:3072
	v_add_u32_e32 v160, s13, v163
	ds_read_b128 v[174:177], v160
	ds_read_b128 v[178:181], v160 offset:1024
	ds_read_b128 v[182:185], v160 offset:2048
	ds_read_b128 v[186:189], v160 offset:3072
	v_lshl_add_u64 v[160:161], s[16:17], 0, v[148:149]
	s_add_i32 m0, s59, 0xc000
	ds_read_b128 v[190:193], v165
	ds_read_b128 v[194:197], v165 offset:1024
	ds_read_b128 v[198:201], v165 offset:2048
	ds_read_b128 v[216:219], v165 offset:3072
	ds_read_b128 v[220:223], v165 offset:4096
	ds_read_b128 v[224:227], v165 offset:5120
	ds_read_b128 v[228:231], v165 offset:6144
	ds_read_b128 v[232:235], v165 offset:7168
	global_load_lds_dwordx4 v[160:161], off
	v_lshl_add_u64 v[160:161], s[16:17], 0, v[150:151]
	s_add_i32 m0, s59, 0xe000
	s_nop 0
	global_load_lds_dwordx4 v[160:161], off
	s_waitcnt vmcnt(8)
	s_waitcnt lgkmcnt(0)
	s_barrier
	v_mfma_f32_16x16x32_bf16 v[126:129], v[152:155], v[190:193], v[126:129]
	v_mfma_f32_16x16x32_bf16 v[122:125], v[166:169], v[190:193], v[122:125]
	v_mfma_f32_16x16x32_bf16 v[110:113], v[152:155], v[198:201], v[110:113]
	v_mfma_f32_16x16x32_bf16 v[106:109], v[166:169], v[198:201], v[106:109]
	v_mfma_f32_16x16x32_bf16 v[94:97], v[152:155], v[220:223], v[94:97]
	v_mfma_f32_16x16x32_bf16 v[90:93], v[166:169], v[220:223], v[90:93]
	v_mfma_f32_16x16x32_bf16 v[78:81], v[152:155], v[228:231], v[78:81]
	v_mfma_f32_16x16x32_bf16 v[74:77], v[166:169], v[228:231], v[74:77]
	v_mfma_f32_16x16x32_bf16 v[126:129], v[156:159], v[194:197], v[126:129]
	v_mfma_f32_16x16x32_bf16 v[122:125], v[170:173], v[194:197], v[122:125]
	v_mfma_f32_16x16x32_bf16 v[110:113], v[156:159], v[216:219], v[110:113]
	v_mfma_f32_16x16x32_bf16 v[106:109], v[170:173], v[216:219], v[106:109]
	v_mfma_f32_16x16x32_bf16 v[94:97], v[156:159], v[224:227], v[94:97]
	v_mfma_f32_16x16x32_bf16 v[90:93], v[170:173], v[224:227], v[90:93]
	v_mfma_f32_16x16x32_bf16 v[78:81], v[156:159], v[232:235], v[78:81]
	v_mfma_f32_16x16x32_bf16 v[74:77], v[170:173], v[232:235], v[74:77]
	v_mfma_f32_16x16x32_bf16 v[118:121], v[174:177], v[190:193], v[118:121]
	v_mfma_f32_16x16x32_bf16 v[114:117], v[182:185], v[190:193], v[114:117]
	v_mfma_f32_16x16x32_bf16 v[102:105], v[174:177], v[198:201], v[102:105]
	v_mfma_f32_16x16x32_bf16 v[98:101], v[182:185], v[198:201], v[98:101]
	v_mfma_f32_16x16x32_bf16 v[86:89], v[174:177], v[220:223], v[86:89]
	v_mfma_f32_16x16x32_bf16 v[82:85], v[182:185], v[220:223], v[82:85]
	v_mfma_f32_16x16x32_bf16 v[70:73], v[174:177], v[228:231], v[70:73]
	v_mfma_f32_16x16x32_bf16 v[66:69], v[182:185], v[228:231], v[66:69]
	v_mfma_f32_16x16x32_bf16 v[118:121], v[178:181], v[194:197], v[118:121]
	v_mfma_f32_16x16x32_bf16 v[114:117], v[186:189], v[194:197], v[114:117]
	v_mfma_f32_16x16x32_bf16 v[102:105], v[178:181], v[216:219], v[102:105]
	v_mfma_f32_16x16x32_bf16 v[98:101], v[186:189], v[216:219], v[98:101]
	v_mfma_f32_16x16x32_bf16 v[86:89], v[178:181], v[224:227], v[86:89]
	v_mfma_f32_16x16x32_bf16 v[82:85], v[186:189], v[224:227], v[82:85]
	v_mfma_f32_16x16x32_bf16 v[70:73], v[178:181], v[232:235], v[70:73]
	v_mfma_f32_16x16x32_bf16 v[66:69], v[186:189], v[232:235], v[66:69]
	s_barrier
	s_add_i32 s10, s12, s58
	v_lshl_add_u64 v[160:161], s[18:19], 0, v[0:1]
	s_mov_b32 m0, s10
	ds_read_b128 v[190:193], v165 offset:16384
	ds_read_b128 v[194:197], v165 offset:17408
	ds_read_b128 v[198:201], v165 offset:18432
	ds_read_b128 v[216:219], v165 offset:19456
	ds_read_b128 v[220:223], v165 offset:20480
	ds_read_b128 v[224:227], v165 offset:21504
	ds_read_b128 v[228:231], v165 offset:22528
	ds_read_b128 v[232:235], v165 offset:23552
	global_load_lds_dwordx4 v[160:161], off
	s_add_i32 m0, s10, 0x2000
	s_add_u32 s10, s18, 0x80000
	v_lshl_add_u64 v[236:237], s[18:19], 0, v[142:143]
	s_addc_u32 s11, s19, 0
	s_add_i32 s12, s13, s58
	global_load_lds_dwordx4 v[236:237], off
	v_lshl_add_u64 v[238:239], s[10:11], 0, v[0:1]
	s_mov_b32 m0, s12
	v_lshl_add_u64 v[240:241], s[24:25], 0, v[144:145]
	global_load_lds_dwordx4 v[238:239], off
	v_lshl_add_u64 v[238:239], s[10:11], 0, v[142:143]
	s_add_i32 m0, s12, 0x2000
	s_nop 0
	global_load_lds_dwordx4 v[238:239], off
	v_lshl_add_u64 v[238:239], s[24:25], 0, v[146:147]
	s_mov_b32 m0, s59
	s_nop 0
	global_load_lds_dwordx4 v[238:239], off
	s_mov_b32 m0, s60
	s_nop 0
	global_load_lds_dwordx4 v[240:241], off
	s_waitcnt vmcnt(8)
	s_waitcnt lgkmcnt(0)
	s_barrier
; #define PG8_STAGE(bufoff, gbase, voff) do { _Pragma("unroll") for (int _i = 0; _i < 2; ++_i) \
;         __builtin_amdgcn_global_load_lds((const unsigned*)((const char*)(gbase) + (voff)[_i]), (PG8_LAS unsigned*)(lds + (bufoff) + ldsw + _i * 8192), 16, 0, 0); } while (0)
; #define PG8_LDA(dst, b, h) do { _Pragma("unroll") for (int m = 0; m < 4; ++m) _Pragma("unroll") for (int k = 0; k < 2; ++k) dst[m][k] = *(const PG8_LAS bf16x8*)(lds + PG8_SA(b, h) + aoff + m * 2048 + k * 1024); } while (0)
; #define PG8_LDB(dst, b, h) do { _Pragma("unroll") for (int n = 0; n < 2; ++n) _Pragma("unroll") for (int k = 0; k < 2; ++k) dst[n][k] = *(const PG8_LAS bf16x8*)(lds + PG8_SB(b, h) + boff + n * 2048 + k * 1024); } while (0)
; #define PG8_MMA(ai, bj, At, Bt) do { __builtin_amdgcn_s_setprio(1); _Pragma("unroll") for (int m = 0; m < 4; ++m) _Pragma("unroll") for (int n = 0; n < 2; ++n) _Pragma("unroll") for (int k = 0; k < 2; ++k) \
;         acc[ai][bj][m][n] = __builtin_amdgcn_mfma_f32_16x16x32_bf16(Bt[n][k], At[m][k], acc[ai][bj][m][n], 0, 0, 0); __builtin_amdgcn_s_setprio(0); } while (0)
; #define PG8_WAIT_V(n) asm volatile("s_waitcnt vmcnt(" #n ")" ::: "memory")
; #define PG8_WAIT_L(n) asm volatile("s_waitcnt lgkmcnt(" #n ")" ::: "memory")
; #define PG8_BAR __builtin_amdgcn_s_barrier()
; #define PG8_SCHED __builtin_amdgcn_sched_barrier(0)
; template <class Epi, class Sched, bool ALIGN_EPI = false, bool SP2 = false>
; __device__ __forceinline__ void gemm_phase(PG8_LAS unsigned char* lds, const Gemm g, const Sched& S, const Epi& E) {
;     ...
;             PG8_WAIT_V(8); PG8_WAIT_L(0); PG8_BAR; PG8_MMA(1, 0, At, B0); PG8_MMA(1, 1, At, B1); PG8_BAR; PG8_SCHED;
;             PG8_LDB(B0, 1, 0); PG8_LDB(B1, 1, 1); PG8_SCHED; PG8_LDA(At, 1, 0); PG8_STAGE(PG8_SA(0, 1), a2 + hstep, voffA);
;             PG8_WAIT_V(8); PG8_WAIT_L(0); PG8_BAR; PG8_MMA(0, 0, At, B0); PG8_MMA(0, 1, At, B1); PG8_BAR; PG8_SCHED;
	v_mfma_f32_16x16x32_bf16 v[62:65], v[152:155], v[190:193], v[62:65]
	v_mfma_f32_16x16x32_bf16 v[58:61], v[166:169], v[190:193], v[58:61]
	v_mfma_f32_16x16x32_bf16 v[46:49], v[152:155], v[198:201], v[46:49]
	v_mfma_f32_16x16x32_bf16 v[42:45], v[166:169], v[198:201], v[42:45]
	v_mfma_f32_16x16x32_bf16 v[30:33], v[152:155], v[220:223], v[30:33]
	v_mfma_f32_16x16x32_bf16 v[26:29], v[166:169], v[220:223], v[26:29]
	v_mfma_f32_16x16x32_bf16 v[14:17], v[152:155], v[228:231], v[14:17]
	v_mfma_f32_16x16x32_bf16 v[10:13], v[166:169], v[228:231], v[10:13]
	v_mfma_f32_16x16x32_bf16 v[62:65], v[156:159], v[194:197], v[62:65]
	v_mfma_f32_16x16x32_bf16 v[58:61], v[170:173], v[194:197], v[58:61]
	v_mfma_f32_16x16x32_bf16 v[46:49], v[156:159], v[216:219], v[46:49]
	v_mfma_f32_16x16x32_bf16 v[42:45], v[170:173], v[216:219], v[42:45]
	v_mfma_f32_16x16x32_bf16 v[30:33], v[156:159], v[224:227], v[30:33]
	v_mfma_f32_16x16x32_bf16 v[26:29], v[170:173], v[224:227], v[26:29]
	v_mfma_f32_16x16x32_bf16 v[14:17], v[156:159], v[232:235], v[14:17]
	v_mfma_f32_16x16x32_bf16 v[10:13], v[170:173], v[232:235], v[10:13]
	v_mfma_f32_16x16x32_bf16 v[54:57], v[174:177], v[190:193], v[54:57]
	v_mfma_f32_16x16x32_bf16 v[50:53], v[182:185], v[190:193], v[50:53]
	v_mfma_f32_16x16x32_bf16 v[38:41], v[174:177], v[198:201], v[38:41]
	v_mfma_f32_16x16x32_bf16 v[34:37], v[182:185], v[198:201], v[34:37]
	v_mfma_f32_16x16x32_bf16 v[22:25], v[174:177], v[220:223], v[22:25]
	v_mfma_f32_16x16x32_bf16 v[18:21], v[182:185], v[220:223], v[18:21]
	v_mfma_f32_16x16x32_bf16 v[6:9], v[174:177], v[228:231], v[6:9]
	v_mfma_f32_16x16x32_bf16 v[2:5], v[182:185], v[228:231], v[2:5]
	v_mfma_f32_16x16x32_bf16 v[54:57], v[178:181], v[194:197], v[54:57]
	v_mfma_f32_16x16x32_bf16 v[50:53], v[186:189], v[194:197], v[50:53]
	v_mfma_f32_16x16x32_bf16 v[38:41], v[178:181], v[216:219], v[38:41]
	v_mfma_f32_16x16x32_bf16 v[34:37], v[186:189], v[216:219], v[34:37]
	v_mfma_f32_16x16x32_bf16 v[22:25], v[178:181], v[224:227], v[22:25]
	v_mfma_f32_16x16x32_bf16 v[18:21], v[186:189], v[224:227], v[18:21]
	v_mfma_f32_16x16x32_bf16 v[6:9], v[178:181], v[232:235], v[6:9]
	v_mfma_f32_16x16x32_bf16 v[2:5], v[186:189], v[232:235], v[2:5]
	s_barrier
	s_add_i32 s12, 0, 0x18000
	s_add_i32 s13, 0, 0x1c000
	v_add_u32_e32 v170, s12, v163
	v_add_u32_e32 v186, s13, v163
	ds_read_b128 v[152:155], v170
	ds_read_b128 v[156:159], v170 offset:1024
	ds_read_b128 v[166:169], v170 offset:2048
	ds_read_b128 v[170:173], v170 offset:3072
	ds_read_b128 v[174:177], v186
	ds_read_b128 v[178:181], v186 offset:1024
	ds_read_b128 v[182:185], v186 offset:2048
	ds_read_b128 v[186:189], v186 offset:3072
	s_add_u32 s10, s24, 0x80000
	s_addc_u32 s11, s25, 0
	s_mov_b32 m0, s61
	v_lshl_add_u64 v[242:243], s[10:11], 0, v[146:147]
	ds_read_b128 v[190:193], v165 offset:32768
	ds_read_b128 v[194:197], v165 offset:33792
	ds_read_b128 v[198:201], v165 offset:34816
	ds_read_b128 v[216:219], v165 offset:35840
	ds_read_b128 v[220:223], v165 offset:36864
	ds_read_b128 v[224:227], v165 offset:37888
	ds_read_b128 v[228:231], v165 offset:38912
	ds_read_b128 v[232:235], v165 offset:39936
	global_load_lds_dwordx4 v[242:243], off
	v_lshl_add_u64 v[242:243], s[10:11], 0, v[144:145]
	s_mov_b32 m0, s62
	s_nop 0
	global_load_lds_dwordx4 v[242:243], off
	s_waitcnt vmcnt(8)
	s_waitcnt lgkmcnt(0)
	s_barrier
	v_mfma_f32_16x16x32_bf16 v[126:129], v[152:155], v[190:193], v[126:129]
	v_mfma_f32_16x16x32_bf16 v[122:125], v[166:169], v[190:193], v[122:125]
	v_mfma_f32_16x16x32_bf16 v[110:113], v[152:155], v[198:201], v[110:113]
	v_mfma_f32_16x16x32_bf16 v[106:109], v[166:169], v[198:201], v[106:109]
	v_mfma_f32_16x16x32_bf16 v[94:97], v[152:155], v[220:223], v[94:97]
	v_mfma_f32_16x16x32_bf16 v[90:93], v[166:169], v[220:223], v[90:93]
	v_mfma_f32_16x16x32_bf16 v[78:81], v[152:155], v[228:231], v[78:81]
	v_mfma_f32_16x16x32_bf16 v[74:77], v[166:169], v[228:231], v[74:77]
	v_mfma_f32_16x16x32_bf16 v[126:129], v[156:159], v[194:197], v[126:129]
	v_mfma_f32_16x16x32_bf16 v[122:125], v[170:173], v[194:197], v[122:125]
	v_mfma_f32_16x16x32_bf16 v[110:113], v[156:159], v[216:219], v[110:113]
	v_mfma_f32_16x16x32_bf16 v[106:109], v[170:173], v[216:219], v[106:109]
	v_mfma_f32_16x16x32_bf16 v[94:97], v[156:159], v[224:227], v[94:97]
	v_mfma_f32_16x16x32_bf16 v[90:93], v[170:173], v[224:227], v[90:93]
	v_mfma_f32_16x16x32_bf16 v[78:81], v[156:159], v[232:235], v[78:81]
	v_mfma_f32_16x16x32_bf16 v[74:77], v[170:173], v[232:235], v[74:77]
	v_mfma_f32_16x16x32_bf16 v[118:121], v[174:177], v[190:193], v[118:121]
	v_mfma_f32_16x16x32_bf16 v[114:117], v[182:185], v[190:193], v[114:117]
	v_mfma_f32_16x16x32_bf16 v[102:105], v[174:177], v[198:201], v[102:105]
	v_mfma_f32_16x16x32_bf16 v[98:101], v[182:185], v[198:201], v[98:101]
	v_mfma_f32_16x16x32_bf16 v[86:89], v[174:177], v[220:223], v[86:89]
	v_mfma_f32_16x16x32_bf16 v[82:85], v[182:185], v[220:223], v[82:85]
	v_mfma_f32_16x16x32_bf16 v[70:73], v[174:177], v[228:231], v[70:73]
	v_mfma_f32_16x16x32_bf16 v[66:69], v[182:185], v[228:231], v[66:69]
	v_mfma_f32_16x16x32_bf16 v[118:121], v[178:181], v[194:197], v[118:121]
	v_mfma_f32_16x16x32_bf16 v[114:117], v[186:189], v[194:197], v[114:117]
	v_mfma_f32_16x16x32_bf16 v[102:105], v[178:181], v[216:219], v[102:105]
	v_mfma_f32_16x16x32_bf16 v[98:101], v[186:189], v[216:219], v[98:101]
	v_mfma_f32_16x16x32_bf16 v[86:89], v[178:181], v[224:227], v[86:89]
	v_mfma_f32_16x16x32_bf16 v[82:85], v[186:189], v[224:227], v[82:85]
	v_mfma_f32_16x16x32_bf16 v[70:73], v[178:181], v[232:235], v[70:73]
	v_mfma_f32_16x16x32_bf16 v[66:69], v[186:189], v[232:235], v[66:69]
	s_barrier
; #define PG8_STAGE(bufoff, gbase, voff) do { _Pragma("unroll") for (int _i = 0; _i < 2; ++_i) \
;         __builtin_amdgcn_global_load_lds((const unsigned*)((const char*)(gbase) + (voff)[_i]), (PG8_LAS unsigned*)(lds + (bufoff) + ldsw + _i * 8192), 16, 0, 0); } while (0)
; #define PG8_LDA(dst, b, h) do { _Pragma("unroll") for (int m = 0; m < 4; ++m) _Pragma("unroll") for (int k = 0; k < 2; ++k) dst[m][k] = *(const PG8_LAS bf16x8*)(lds + PG8_SA(b, h) + aoff + m * 2048 + k * 1024); } while (0)
; #define PG8_MMA(ai, bj, At, Bt) do { __builtin_amdgcn_s_setprio(1); _Pragma("unroll") for (int m = 0; m < 4; ++m) _Pragma("unroll") for (int n = 0; n < 2; ++n) _Pragma("unroll") for (int k = 0; k < 2; ++k) \
;         acc[ai][bj][m][n] = __builtin_amdgcn_mfma_f32_16x16x32_bf16(Bt[n][k], At[m][k], acc[ai][bj][m][n], 0, 0, 0); __builtin_amdgcn_s_setprio(0); } while (0)
; #define PG8_WAIT_V(n) asm volatile("s_waitcnt vmcnt(" #n ")" ::: "memory")
; #define PG8_WAIT_L(n) asm volatile("s_waitcnt lgkmcnt(" #n ")" ::: "memory")
; #define PG8_BAR __builtin_amdgcn_s_barrier()
; #define PG8_SCHED __builtin_amdgcn_sched_barrier(0)
; template <class Epi, class Sched, bool ALIGN_EPI = false, bool SP2 = false>
; __device__ __forceinline__ void gemm_phase(PG8_LAS unsigned char* lds, const Gemm g, const Sched& S, const Epi& E) {
;     ...
;             PG8_LDA(At, 1, 1); PG8_STAGE(PG8_SB(1, 0), b3, voffB); PG8_STAGE(PG8_SB(1, 1), b3 + hstep, voffB); PG8_STAGE(PG8_SA(1, 0), a3, voffA);
;             PG8_WAIT_V(8); PG8_WAIT_L(0); PG8_BAR; PG8_MMA(1, 0, At, B0); PG8_MMA(1, 1, At, B1); PG8_BAR; PG8_SCHED;
;     ...
;         if constexpr (ALIGN_EPI) { if (wr == 0) PG8_BAR; }
	s_add_i32 s10, s12, s58
	v_lshl_add_u64 v[160:161], v[160:161], 0, s[30:31]
	s_mov_b32 m0, s10
	ds_read_b128 v[190:193], v165 offset:49152
	ds_read_b128 v[194:197], v165 offset:50176
	ds_read_b128 v[198:201], v165 offset:51200
	ds_read_b128 v[216:219], v165 offset:52224
	ds_read_b128 v[220:223], v165 offset:53248
	ds_read_b128 v[224:227], v165 offset:54272
	ds_read_b128 v[228:231], v165 offset:55296
	ds_read_b128 v[232:235], v165 offset:56320
	global_load_lds_dwordx4 v[160:161], off
	s_add_i32 m0, s10, 0x2000
	s_add_u32 s10, s18, 0x80080
	v_lshl_add_u64 v[160:161], v[236:237], 0, s[30:31]
	s_addc_u32 s11, s19, 0
	s_add_i32 s12, s13, s58
	global_load_lds_dwordx4 v[160:161], off
	v_lshl_add_u64 v[160:161], s[10:11], 0, v[0:1]
	s_mov_b32 m0, s12
	s_nop 0
	global_load_lds_dwordx4 v[160:161], off
	v_lshl_add_u64 v[160:161], s[10:11], 0, v[142:143]
	s_add_i32 m0, s12, 0x2000
	s_nop 0
	global_load_lds_dwordx4 v[160:161], off
	v_lshl_add_u64 v[160:161], v[238:239], 0, s[30:31]
	s_mov_b32 m0, s63
	s_nop 0
	global_load_lds_dwordx4 v[160:161], off
	v_lshl_add_u64 v[160:161], v[240:241], 0, s[30:31]
	s_mov_b32 m0, s64
	s_nop 0
	global_load_lds_dwordx4 v[160:161], off
	s_waitcnt vmcnt(8)
	s_waitcnt lgkmcnt(0)
	s_barrier
	v_mfma_f32_16x16x32_bf16 v[62:65], v[152:155], v[190:193], v[62:65]
	v_mfma_f32_16x16x32_bf16 v[58:61], v[166:169], v[190:193], v[58:61]
	v_mfma_f32_16x16x32_bf16 v[46:49], v[152:155], v[198:201], v[46:49]
	v_mfma_f32_16x16x32_bf16 v[42:45], v[166:169], v[198:201], v[42:45]
	v_mfma_f32_16x16x32_bf16 v[30:33], v[152:155], v[220:223], v[30:33]
	v_mfma_f32_16x16x32_bf16 v[26:29], v[166:169], v[220:223], v[26:29]
	v_mfma_f32_16x16x32_bf16 v[14:17], v[152:155], v[228:231], v[14:17]
	v_mfma_f32_16x16x32_bf16 v[10:13], v[166:169], v[228:231], v[10:13]
	v_mfma_f32_16x16x32_bf16 v[62:65], v[156:159], v[194:197], v[62:65]
	v_mfma_f32_16x16x32_bf16 v[58:61], v[170:173], v[194:197], v[58:61]
	v_mfma_f32_16x16x32_bf16 v[46:49], v[156:159], v[216:219], v[46:49]
	v_mfma_f32_16x16x32_bf16 v[42:45], v[170:173], v[216:219], v[42:45]
	v_mfma_f32_16x16x32_bf16 v[30:33], v[156:159], v[224:227], v[30:33]
	v_mfma_f32_16x16x32_bf16 v[26:29], v[170:173], v[224:227], v[26:29]
	v_mfma_f32_16x16x32_bf16 v[14:17], v[156:159], v[232:235], v[14:17]
	v_mfma_f32_16x16x32_bf16 v[10:13], v[170:173], v[232:235], v[10:13]
	v_mfma_f32_16x16x32_bf16 v[54:57], v[174:177], v[190:193], v[54:57]
	v_mfma_f32_16x16x32_bf16 v[50:53], v[182:185], v[190:193], v[50:53]
	v_mfma_f32_16x16x32_bf16 v[38:41], v[174:177], v[198:201], v[38:41]
	v_mfma_f32_16x16x32_bf16 v[34:37], v[182:185], v[198:201], v[34:37]
	v_mfma_f32_16x16x32_bf16 v[22:25], v[174:177], v[220:223], v[22:25]
	v_mfma_f32_16x16x32_bf16 v[18:21], v[182:185], v[220:223], v[18:21]
	v_mfma_f32_16x16x32_bf16 v[6:9], v[174:177], v[228:231], v[6:9]
	v_mfma_f32_16x16x32_bf16 v[2:5], v[182:185], v[228:231], v[2:5]
	v_mfma_f32_16x16x32_bf16 v[54:57], v[178:181], v[194:197], v[54:57]
	v_mfma_f32_16x16x32_bf16 v[50:53], v[186:189], v[194:197], v[50:53]
	v_mfma_f32_16x16x32_bf16 v[38:41], v[178:181], v[216:219], v[38:41]
	v_mfma_f32_16x16x32_bf16 v[34:37], v[186:189], v[216:219], v[34:37]
	v_mfma_f32_16x16x32_bf16 v[22:25], v[178:181], v[224:227], v[22:25]
	v_mfma_f32_16x16x32_bf16 v[18:21], v[186:189], v[224:227], v[18:21]
	v_mfma_f32_16x16x32_bf16 v[6:9], v[178:181], v[232:235], v[6:9]
	v_mfma_f32_16x16x32_bf16 v[2:5], v[186:189], v[232:235], v[2:5]
	s_barrier
	s_add_i32 s22, s22, 2
	s_add_u32 s16, s16, 0x100
	s_addc_u32 s17, s17, 0
	s_add_u32 s14, s14, 0x100
	s_addc_u32 s15, s15, 0
	s_cmp_gt_u32 s22, 29
	s_cbranch_scc0 .LBB0_686
	s_and_b64 vcc, exec, s[50:51]
	s_cbranch_vccz .LBB0_689
	s_barrier

; #define PG8_STAGE(bufoff, gbase, voff) do { _Pragma("unroll") for (int _i = 0; _i < 2; ++_i) \
;         __builtin_amdgcn_global_load_lds((const unsigned*)((const char*)(gbase) + (voff)[_i]), (PG8_LAS unsigned*)(lds + (bufoff) + ldsw + _i * 8192), 16, 0, 0); } while (0)
; #define PG8_LDA(dst, b, h) do { _Pragma("unroll") for (int m = 0; m < 4; ++m) _Pragma("unroll") for (int k = 0; k < 2; ++k) dst[m][k] = *(const PG8_LAS bf16x8*)(lds + PG8_SA(b, h) + aoff + m * 2048 + k * 1024); } while (0)
; #define PG8_LDB(dst, b, h) do { _Pragma("unroll") for (int n = 0; n < 2; ++n) _Pragma("unroll") for (int k = 0; k < 2; ++k) dst[n][k] = *(const PG8_LAS bf16x8*)(lds + PG8_SB(b, h) + boff + n * 2048 + k * 1024); } while (0)
; #define PG8_MMA(ai, bj, At, Bt) do { __builtin_amdgcn_s_setprio(1); _Pragma("unroll") for (int m = 0; m < 4; ++m) _Pragma("unroll") for (int n = 0; n < 2; ++n) _Pragma("unroll") for (int k = 0; k < 2; ++k) \
;         acc[ai][bj][m][n] = __builtin_amdgcn_mfma_f32_16x16x32_bf16(Bt[n][k], At[m][k], acc[ai][bj][m][n], 0, 0, 0); __builtin_amdgcn_s_setprio(0); } while (0)
; #define PG8_WAIT_V(n) asm volatile("s_waitcnt vmcnt(" #n ")" ::: "memory")
; #define PG8_WAIT_L(n) asm volatile("s_waitcnt lgkmcnt(" #n ")" ::: "memory")
; template <class Epi, class Sched, bool ALIGN_EPI = false, bool SP2 = false>
; __device__ __forceinline__ void gemm_phase(PG8_LAS unsigned char* lds, const Gemm g, const Sched& S, const Epi& E) {
;     ...
;             const bool last = (t == nt - 2);
;             const char* a1 = cA + (size_t)(t + 1) * kstep;
;             const char* a2 = last ? nA : cA + (size_t)(t + 2) * kstep; const char* b2 = last ? nB : cB + (size_t)(t + 2) * kstep;
;             const char* a3 = a2 + kstep; const char* b3 = b2 + kstep;
;             if (last && has_next) S.a_ready(nxt);
;             if constexpr (SP2) {
;             PG8_LDB(B0, 0, 0); PG8_LDB(B1, 0, 1); PG8_SCHED; PG8_LDA(At, 0, 0); PG8_STAGE(PG8_SA(1, 1), a1 + hstep, voffA);
;             PG8_WAIT_V(8); PG8_WAIT_L(0); PG8_BAR; PG8_MMA(0, 0, At, B0); PG8_MMA(0, 1, At, B1); PG8_BAR; PG8_SCHED;
;             PG8_LDA(At, 0, 1); PG8_STAGE(PG8_SB(0, 0), b2, voffB); PG8_STAGE(PG8_SB(0, 1), b2 + hstep, voffB); PG8_STAGE(PG8_SA(0, 0), a2, voffA);
;             PG8_WAIT_V(8); PG8_WAIT_L(0); PG8_BAR; PG8_MMA(1, 0, At, B0); PG8_MMA(1, 1, At, B1); PG8_BAR; PG8_SCHED;
.LBB0_758:
	s_add_u32 s18, s16, 0x100
	s_addc_u32 s19, s17, 0
	s_add_i32 s10, 0, 0x10000
	s_cmpk_eq_i32 s22, 0x7c
	s_cselect_b32 s27, s5, s19
	s_cselect_b32 s26, s7, s18
	s_cselect_b32 s25, s8, s15
	s_cselect_b32 s24, s9, s14
	s_add_i32 s12, 0, 0x14000
	v_add_u32_e32 v160, s10, v216
	v_add_u32_e32 v176, s12, v216
	ds_read_b128 v[148:151], v160
	ds_read_b128 v[152:155], v160 offset:1024
	ds_read_b128 v[156:159], v160 offset:2048
	ds_read_b128 v[160:163], v160 offset:3072
	ds_read_b128 v[164:167], v176
	ds_read_b128 v[168:171], v176 offset:1024
	ds_read_b128 v[172:175], v176 offset:2048
	ds_read_b128 v[176:179], v176 offset:3072
	v_lshl_add_u64 v[200:201], s[16:17], 0, v[144:145]
	s_add_i32 m0, s64, 0xc000
	ds_read_b128 v[180:183], v218
	ds_read_b128 v[184:187], v218 offset:1024
	ds_read_b128 v[188:191], v218 offset:2048
	ds_read_b128 v[192:195], v218 offset:3072
	ds_read_b128 v[196:199], v218 offset:4096
	ds_read_b128 v[220:223], v218 offset:5120
	ds_read_b128 v[224:227], v218 offset:6144
	ds_read_b128 v[228:231], v218 offset:7168
	global_load_lds_dwordx4 v[200:201], off
	v_lshl_add_u64 v[200:201], s[16:17], 0, v[146:147]
	s_add_i32 m0, s64, 0xe000
	s_nop 0
	global_load_lds_dwordx4 v[200:201], off
	s_waitcnt vmcnt(8)
	s_waitcnt lgkmcnt(0)
	s_barrier
	v_mfma_f32_16x16x32_bf16 v[126:129], v[148:151], v[180:183], v[126:129]
	v_mfma_f32_16x16x32_bf16 v[122:125], v[156:159], v[180:183], v[122:125]
	v_mfma_f32_16x16x32_bf16 v[110:113], v[148:151], v[188:191], v[110:113]
	v_mfma_f32_16x16x32_bf16 v[106:109], v[156:159], v[188:191], v[106:109]
	v_mfma_f32_16x16x32_bf16 v[94:97], v[148:151], v[196:199], v[94:97]
	v_mfma_f32_16x16x32_bf16 v[90:93], v[156:159], v[196:199], v[90:93]
	v_mfma_f32_16x16x32_bf16 v[78:81], v[148:151], v[224:227], v[78:81]
	v_mfma_f32_16x16x32_bf16 v[74:77], v[156:159], v[224:227], v[74:77]
	v_mfma_f32_16x16x32_bf16 v[126:129], v[152:155], v[184:187], v[126:129]
	v_mfma_f32_16x16x32_bf16 v[122:125], v[160:163], v[184:187], v[122:125]
	v_mfma_f32_16x16x32_bf16 v[110:113], v[152:155], v[192:195], v[110:113]
	v_mfma_f32_16x16x32_bf16 v[106:109], v[160:163], v[192:195], v[106:109]
	v_mfma_f32_16x16x32_bf16 v[94:97], v[152:155], v[220:223], v[94:97]
	v_mfma_f32_16x16x32_bf16 v[90:93], v[160:163], v[220:223], v[90:93]
	v_mfma_f32_16x16x32_bf16 v[78:81], v[152:155], v[228:231], v[78:81]
	v_mfma_f32_16x16x32_bf16 v[74:77], v[160:163], v[228:231], v[74:77]
	v_mfma_f32_16x16x32_bf16 v[118:121], v[164:167], v[180:183], v[118:121]
	v_mfma_f32_16x16x32_bf16 v[114:117], v[172:175], v[180:183], v[114:117]
	v_mfma_f32_16x16x32_bf16 v[102:105], v[164:167], v[188:191], v[102:105]
	v_mfma_f32_16x16x32_bf16 v[98:101], v[172:175], v[188:191], v[98:101]
	v_mfma_f32_16x16x32_bf16 v[86:89], v[164:167], v[196:199], v[86:89]
	v_mfma_f32_16x16x32_bf16 v[82:85], v[172:175], v[196:199], v[82:85]
	v_mfma_f32_16x16x32_bf16 v[70:73], v[164:167], v[224:227], v[70:73]
	v_mfma_f32_16x16x32_bf16 v[66:69], v[172:175], v[224:227], v[66:69]
	v_mfma_f32_16x16x32_bf16 v[118:121], v[168:171], v[184:187], v[118:121]
	v_mfma_f32_16x16x32_bf16 v[114:117], v[176:179], v[184:187], v[114:117]
	v_mfma_f32_16x16x32_bf16 v[102:105], v[168:171], v[192:195], v[102:105]
	v_mfma_f32_16x16x32_bf16 v[98:101], v[176:179], v[192:195], v[98:101]
	v_mfma_f32_16x16x32_bf16 v[86:89], v[168:171], v[220:223], v[86:89]
	v_mfma_f32_16x16x32_bf16 v[82:85], v[176:179], v[220:223], v[82:85]
	v_mfma_f32_16x16x32_bf16 v[70:73], v[168:171], v[228:231], v[70:73]
	v_mfma_f32_16x16x32_bf16 v[66:69], v[176:179], v[228:231], v[66:69]
	s_barrier
	s_add_i32 s10, s10, s63
	v_lshl_add_u64 v[200:201], s[24:25], 0, v[0:1]
	s_mov_b32 m0, s10
	ds_read_b128 v[180:183], v218 offset:16384
	ds_read_b128 v[184:187], v218 offset:17408
	ds_read_b128 v[188:191], v218 offset:18432
	ds_read_b128 v[192:195], v218 offset:19456
	ds_read_b128 v[196:199], v218 offset:20480
	ds_read_b128 v[220:223], v218 offset:21504
	ds_read_b128 v[224:227], v218 offset:22528
	ds_read_b128 v[228:231], v218 offset:23552
	global_load_lds_dwordx4 v[200:201], off
	s_add_i32 m0, s10, 0x2000
	s_add_u32 s10, s24, 0x200000
	v_lshl_add_u64 v[232:233], s[24:25], 0, v[142:143]
	s_addc_u32 s11, s25, 0
	s_add_i32 s12, s12, s63
	global_load_lds_dwordx4 v[232:233], off
	v_lshl_add_u64 v[234:235], s[10:11], 0, v[0:1]
	s_mov_b32 m0, s12
	v_lshl_add_u64 v[236:237], s[26:27], 0, v[142:143]
	global_load_lds_dwordx4 v[234:235], off
	v_lshl_add_u64 v[234:235], s[10:11], 0, v[142:143]
	s_add_i32 m0, s12, 0x2000
	s_nop 0
	global_load_lds_dwordx4 v[234:235], off
	v_lshl_add_u64 v[234:235], s[26:27], 0, v[0:1]
	s_mov_b32 m0, s64
	s_nop 0
	global_load_lds_dwordx4 v[234:235], off
	s_mov_b32 m0, s65
	s_nop 0
	global_load_lds_dwordx4 v[236:237], off
	s_waitcnt vmcnt(8)
	s_waitcnt lgkmcnt(0)
	s_barrier
; #define PG8_STAGE(bufoff, gbase, voff) do { _Pragma("unroll") for (int _i = 0; _i < 2; ++_i) \
;         __builtin_amdgcn_global_load_lds((const unsigned*)((const char*)(gbase) + (voff)[_i]), (PG8_LAS unsigned*)(lds + (bufoff) + ldsw + _i * 8192), 16, 0, 0); } while (0)
; #define PG8_LDA(dst, b, h) do { _Pragma("unroll") for (int m = 0; m < 4; ++m) _Pragma("unroll") for (int k = 0; k < 2; ++k) dst[m][k] = *(const PG8_LAS bf16x8*)(lds + PG8_SA(b, h) + aoff + m * 2048 + k * 1024); } while (0)
; #define PG8_LDB(dst, b, h) do { _Pragma("unroll") for (int n = 0; n < 2; ++n) _Pragma("unroll") for (int k = 0; k < 2; ++k) dst[n][k] = *(const PG8_LAS bf16x8*)(lds + PG8_SB(b, h) + boff + n * 2048 + k * 1024); } while (0)
; #define PG8_MMA(ai, bj, At, Bt) do { __builtin_amdgcn_s_setprio(1); _Pragma("unroll") for (int m = 0; m < 4; ++m) _Pragma("unroll") for (int n = 0; n < 2; ++n) _Pragma("unroll") for (int k = 0; k < 2; ++k) \
;         acc[ai][bj][m][n] = __builtin_amdgcn_mfma_f32_16x16x32_bf16(Bt[n][k], At[m][k], acc[ai][bj][m][n], 0, 0, 0); __builtin_amdgcn_s_setprio(0); } while (0)
; #define PG8_WAIT_V(n) asm volatile("s_waitcnt vmcnt(" #n ")" ::: "memory")
; #define PG8_WAIT_L(n) asm volatile("s_waitcnt lgkmcnt(" #n ")" ::: "memory")
; #define PG8_BAR __builtin_amdgcn_s_barrier()
; #define PG8_SCHED __builtin_amdgcn_sched_barrier(0)
; template <class Epi, class Sched, bool ALIGN_EPI = false, bool SP2 = false>
; __device__ __forceinline__ void gemm_phase(PG8_LAS unsigned char* lds, const Gemm g, const Sched& S, const Epi& E) {
;     ...
;             PG8_WAIT_V(8); PG8_WAIT_L(0); PG8_BAR; PG8_MMA(1, 0, At, B0); PG8_MMA(1, 1, At, B1); PG8_BAR; PG8_SCHED;
;             PG8_LDB(B0, 1, 0); PG8_LDB(B1, 1, 1); PG8_SCHED; PG8_LDA(At, 1, 0); PG8_STAGE(PG8_SA(0, 1), a2 + hstep, voffA);
;             PG8_WAIT_V(8); PG8_WAIT_L(0); PG8_BAR; PG8_MMA(0, 0, At, B0); PG8_MMA(0, 1, At, B1); PG8_BAR; PG8_SCHED;
	v_mfma_f32_16x16x32_bf16 v[62:65], v[148:151], v[180:183], v[62:65]
	v_mfma_f32_16x16x32_bf16 v[58:61], v[156:159], v[180:183], v[58:61]
	v_mfma_f32_16x16x32_bf16 v[46:49], v[148:151], v[188:191], v[46:49]
	v_mfma_f32_16x16x32_bf16 v[42:45], v[156:159], v[188:191], v[42:45]
	v_mfma_f32_16x16x32_bf16 v[30:33], v[148:151], v[196:199], v[30:33]
	v_mfma_f32_16x16x32_bf16 v[26:29], v[156:159], v[196:199], v[26:29]
	v_mfma_f32_16x16x32_bf16 v[14:17], v[148:151], v[224:227], v[14:17]
	v_mfma_f32_16x16x32_bf16 v[10:13], v[156:159], v[224:227], v[10:13]
	v_mfma_f32_16x16x32_bf16 v[62:65], v[152:155], v[184:187], v[62:65]
	v_mfma_f32_16x16x32_bf16 v[58:61], v[160:163], v[184:187], v[58:61]
	v_mfma_f32_16x16x32_bf16 v[46:49], v[152:155], v[192:195], v[46:49]
	v_mfma_f32_16x16x32_bf16 v[42:45], v[160:163], v[192:195], v[42:45]
	v_mfma_f32_16x16x32_bf16 v[30:33], v[152:155], v[220:223], v[30:33]
	v_mfma_f32_16x16x32_bf16 v[26:29], v[160:163], v[220:223], v[26:29]
	v_mfma_f32_16x16x32_bf16 v[14:17], v[152:155], v[228:231], v[14:17]
	v_mfma_f32_16x16x32_bf16 v[10:13], v[160:163], v[228:231], v[10:13]
	v_mfma_f32_16x16x32_bf16 v[54:57], v[164:167], v[180:183], v[54:57]
	v_mfma_f32_16x16x32_bf16 v[50:53], v[172:175], v[180:183], v[50:53]
	v_mfma_f32_16x16x32_bf16 v[38:41], v[164:167], v[188:191], v[38:41]
	v_mfma_f32_16x16x32_bf16 v[34:37], v[172:175], v[188:191], v[34:37]
	v_mfma_f32_16x16x32_bf16 v[22:25], v[164:167], v[196:199], v[22:25]
	v_mfma_f32_16x16x32_bf16 v[18:21], v[172:175], v[196:199], v[18:21]
	v_mfma_f32_16x16x32_bf16 v[6:9], v[164:167], v[224:227], v[6:9]
	v_mfma_f32_16x16x32_bf16 v[2:5], v[172:175], v[224:227], v[2:5]
	v_mfma_f32_16x16x32_bf16 v[54:57], v[168:171], v[184:187], v[54:57]
	v_mfma_f32_16x16x32_bf16 v[50:53], v[176:179], v[184:187], v[50:53]
	v_mfma_f32_16x16x32_bf16 v[38:41], v[168:171], v[192:195], v[38:41]
	v_mfma_f32_16x16x32_bf16 v[34:37], v[176:179], v[192:195], v[34:37]
	v_mfma_f32_16x16x32_bf16 v[22:25], v[168:171], v[220:223], v[22:25]
	v_mfma_f32_16x16x32_bf16 v[18:21], v[176:179], v[220:223], v[18:21]
	v_mfma_f32_16x16x32_bf16 v[6:9], v[168:171], v[228:231], v[6:9]
	v_mfma_f32_16x16x32_bf16 v[2:5], v[176:179], v[228:231], v[2:5]
	s_barrier
	s_add_i32 s12, 0, 0x18000
	s_add_i32 s13, 0, 0x1c000
	v_add_u32_e32 v160, s12, v216
	v_add_u32_e32 v176, s13, v216
	ds_read_b128 v[148:151], v160
	ds_read_b128 v[152:155], v160 offset:1024
	ds_read_b128 v[156:159], v160 offset:2048
	ds_read_b128 v[160:163], v160 offset:3072
	ds_read_b128 v[164:167], v176
	ds_read_b128 v[168:171], v176 offset:1024
	ds_read_b128 v[172:175], v176 offset:2048
	ds_read_b128 v[176:179], v176 offset:3072
	s_add_u32 s10, s26, 0x200000
	s_addc_u32 s11, s27, 0
	s_mov_b32 m0, s66
	v_lshl_add_u64 v[238:239], s[10:11], 0, v[0:1]
	ds_read_b128 v[180:183], v218 offset:32768
	ds_read_b128 v[184:187], v218 offset:33792
	ds_read_b128 v[188:191], v218 offset:34816
	ds_read_b128 v[192:195], v218 offset:35840
	ds_read_b128 v[196:199], v218 offset:36864
	ds_read_b128 v[220:223], v218 offset:37888
	ds_read_b128 v[224:227], v218 offset:38912
	ds_read_b128 v[228:231], v218 offset:39936
	global_load_lds_dwordx4 v[238:239], off
	v_lshl_add_u64 v[238:239], s[10:11], 0, v[142:143]
	s_mov_b32 m0, s67
	s_nop 0
	global_load_lds_dwordx4 v[238:239], off
	s_waitcnt vmcnt(8)
	s_waitcnt lgkmcnt(0)
	s_barrier
	v_mfma_f32_16x16x32_bf16 v[126:129], v[148:151], v[180:183], v[126:129]
	v_mfma_f32_16x16x32_bf16 v[122:125], v[156:159], v[180:183], v[122:125]
	v_mfma_f32_16x16x32_bf16 v[110:113], v[148:151], v[188:191], v[110:113]
	v_mfma_f32_16x16x32_bf16 v[106:109], v[156:159], v[188:191], v[106:109]
	v_mfma_f32_16x16x32_bf16 v[94:97], v[148:151], v[196:199], v[94:97]
	v_mfma_f32_16x16x32_bf16 v[90:93], v[156:159], v[196:199], v[90:93]
	v_mfma_f32_16x16x32_bf16 v[78:81], v[148:151], v[224:227], v[78:81]
	v_mfma_f32_16x16x32_bf16 v[74:77], v[156:159], v[224:227], v[74:77]
	v_mfma_f32_16x16x32_bf16 v[126:129], v[152:155], v[184:187], v[126:129]
	v_mfma_f32_16x16x32_bf16 v[122:125], v[160:163], v[184:187], v[122:125]
	v_mfma_f32_16x16x32_bf16 v[110:113], v[152:155], v[192:195], v[110:113]
	v_mfma_f32_16x16x32_bf16 v[106:109], v[160:163], v[192:195], v[106:109]
	v_mfma_f32_16x16x32_bf16 v[94:97], v[152:155], v[220:223], v[94:97]
	v_mfma_f32_16x16x32_bf16 v[90:93], v[160:163], v[220:223], v[90:93]
	v_mfma_f32_16x16x32_bf16 v[78:81], v[152:155], v[228:231], v[78:81]
	v_mfma_f32_16x16x32_bf16 v[74:77], v[160:163], v[228:231], v[74:77]
	v_mfma_f32_16x16x32_bf16 v[118:121], v[164:167], v[180:183], v[118:121]
	v_mfma_f32_16x16x32_bf16 v[114:117], v[172:175], v[180:183], v[114:117]
	v_mfma_f32_16x16x32_bf16 v[102:105], v[164:167], v[188:191], v[102:105]
	v_mfma_f32_16x16x32_bf16 v[98:101], v[172:175], v[188:191], v[98:101]
	v_mfma_f32_16x16x32_bf16 v[86:89], v[164:167], v[196:199], v[86:89]
	v_mfma_f32_16x16x32_bf16 v[82:85], v[172:175], v[196:199], v[82:85]
	v_mfma_f32_16x16x32_bf16 v[70:73], v[164:167], v[224:227], v[70:73]
	v_mfma_f32_16x16x32_bf16 v[66:69], v[172:175], v[224:227], v[66:69]
	v_mfma_f32_16x16x32_bf16 v[118:121], v[168:171], v[184:187], v[118:121]
	v_mfma_f32_16x16x32_bf16 v[114:117], v[176:179], v[184:187], v[114:117]
	v_mfma_f32_16x16x32_bf16 v[102:105], v[168:171], v[192:195], v[102:105]
	v_mfma_f32_16x16x32_bf16 v[98:101], v[176:179], v[192:195], v[98:101]
	v_mfma_f32_16x16x32_bf16 v[86:89], v[168:171], v[220:223], v[86:89]
	v_mfma_f32_16x16x32_bf16 v[82:85], v[176:179], v[220:223], v[82:85]
	v_mfma_f32_16x16x32_bf16 v[70:73], v[168:171], v[228:231], v[70:73]
	v_mfma_f32_16x16x32_bf16 v[66:69], v[176:179], v[228:231], v[66:69]
	s_barrier
; #define PG8_STAGE(bufoff, gbase, voff) do { _Pragma("unroll") for (int _i = 0; _i < 2; ++_i) \
;         __builtin_amdgcn_global_load_lds((const unsigned*)((const char*)(gbase) + (voff)[_i]), (PG8_LAS unsigned*)(lds + (bufoff) + ldsw + _i * 8192), 16, 0, 0); } while (0)
; #define PG8_LDA(dst, b, h) do { _Pragma("unroll") for (int m = 0; m < 4; ++m) _Pragma("unroll") for (int k = 0; k < 2; ++k) dst[m][k] = *(const PG8_LAS bf16x8*)(lds + PG8_SA(b, h) + aoff + m * 2048 + k * 1024); } while (0)
; #define PG8_WAIT_V(n) asm volatile("s_waitcnt vmcnt(" #n ")" ::: "memory")
; #define PG8_WAIT_L(n) asm volatile("s_waitcnt lgkmcnt(" #n ")" ::: "memory")
;     __device__ __forceinline__ void operator()(const f32x4 (&acc)[2][2][4][2], const Unit& u, int wr, int wc, int fr, int fq) const {
;     ...
;             for (int m = 0; m < 4; ++m) { const size_t off = (size_t)(row0 + ai * HALF + m * 16) * ldc + col0;
; #pragma unroll
;                 for (int bj = 0; bj < 2; ++bj)
; #pragma unroll
;                     for (int n = 0; n < 2; ++n) bv[m][bj][n] = *(const u32x2*)(xb + off + bj * HALF + n * 16); }
;             asm volatile("" ::: "memory");
; #pragma unroll
;             for (int m = 0; m < 4; ++m) {
;                 const int row = row0 + ai * HALF + m * 16;
;                 const size_t off = (size_t)row * ldc + col0;
;                 float s = 0.f;
; #pragma unroll
;                 for (int bj = 0; bj < 2; ++bj)
; #pragma unroll
;                     for (int n = 0; n < 2; ++n) {
;                         const size_t c = off + bj * HALF + n * 16;
;                         const u32x2 w0 = bv[m][bj][n];
;                         const f32x4 b = {__uint_as_float(w0.x << 16), __uint_as_float(w0.x & 0xffff0000u), __uint_as_float(w0.y << 16), __uint_as_float(w0.y & 0xffff0000u)};
;                         const f32x4 o = b + acc[ai][bj][m][n];
;                         if (fin) { *(f32x4*)(outf + c) = o; }
; template <class Epi, class Sched, bool ALIGN_EPI = false, bool SP2 = false>
; __device__ __forceinline__ void gemm_phase(PG8_LAS unsigned char* lds, const Gemm g, const Sched& S, const Epi& E) {
;     ...
;             PG8_LDA(At, 1, 1); PG8_STAGE(PG8_SB(1, 0), b3, voffB); PG8_STAGE(PG8_SB(1, 1), b3 + hstep, voffB); PG8_STAGE(PG8_SA(1, 0), a3, voffA);
;             PG8_WAIT_V(8); PG8_WAIT_L(0); PG8_BAR; PG8_MMA(1, 0, At, B0); PG8_MMA(1, 1, At, B1); PG8_BAR; PG8_SCHED;
	s_add_i32 s10, s12, s63
	v_lshl_add_u64 v[200:201], v[200:201], 0, s[30:31]
	s_mov_b32 m0, s10
	ds_read_b128 v[180:183], v218 offset:49152
	ds_read_b128 v[184:187], v218 offset:50176
	ds_read_b128 v[188:191], v218 offset:51200
	ds_read_b128 v[192:195], v218 offset:52224
	ds_read_b128 v[196:199], v218 offset:53248
	ds_read_b128 v[220:223], v218 offset:54272
	ds_read_b128 v[224:227], v218 offset:55296
	ds_read_b128 v[228:231], v218 offset:56320
	global_load_lds_dwordx4 v[200:201], off
	s_add_i32 m0, s10, 0x2000
	s_add_u32 s10, s24, 0x200080
	v_lshl_add_u64 v[200:201], v[232:233], 0, s[30:31]
	s_addc_u32 s11, s25, 0
	s_add_i32 s12, s13, s63
	global_load_lds_dwordx4 v[200:201], off
	v_lshl_add_u64 v[200:201], s[10:11], 0, v[0:1]
	s_mov_b32 m0, s12
	s_nop 0
	global_load_lds_dwordx4 v[200:201], off
	v_lshl_add_u64 v[200:201], s[10:11], 0, v[142:143]
	s_add_i32 m0, s12, 0x2000
	s_nop 0
	global_load_lds_dwordx4 v[200:201], off
	v_lshl_add_u64 v[200:201], v[234:235], 0, s[30:31]
	s_mov_b32 m0, s68
	s_nop 0
	global_load_lds_dwordx4 v[200:201], off
	v_lshl_add_u64 v[200:201], v[236:237], 0, s[30:31]
	s_mov_b32 m0, s69
	s_nop 0
	global_load_lds_dwordx4 v[200:201], off
	s_waitcnt vmcnt(8)
	s_waitcnt lgkmcnt(0)
	s_barrier
	v_mfma_f32_16x16x32_bf16 v[62:65], v[148:151], v[180:183], v[62:65]
	v_mfma_f32_16x16x32_bf16 v[58:61], v[156:159], v[180:183], v[58:61]
	v_mfma_f32_16x16x32_bf16 v[46:49], v[148:151], v[188:191], v[46:49]
	v_mfma_f32_16x16x32_bf16 v[42:45], v[156:159], v[188:191], v[42:45]
	v_mfma_f32_16x16x32_bf16 v[30:33], v[148:151], v[196:199], v[30:33]
	v_mfma_f32_16x16x32_bf16 v[26:29], v[156:159], v[196:199], v[26:29]
	v_mfma_f32_16x16x32_bf16 v[14:17], v[148:151], v[224:227], v[14:17]
	v_mfma_f32_16x16x32_bf16 v[10:13], v[156:159], v[224:227], v[10:13]
	v_mfma_f32_16x16x32_bf16 v[62:65], v[152:155], v[184:187], v[62:65]
	v_mfma_f32_16x16x32_bf16 v[58:61], v[160:163], v[184:187], v[58:61]
	v_mfma_f32_16x16x32_bf16 v[46:49], v[152:155], v[192:195], v[46:49]
	v_mfma_f32_16x16x32_bf16 v[42:45], v[160:163], v[192:195], v[42:45]
	v_mfma_f32_16x16x32_bf16 v[30:33], v[152:155], v[220:223], v[30:33]
	v_mfma_f32_16x16x32_bf16 v[26:29], v[160:163], v[220:223], v[26:29]
	v_mfma_f32_16x16x32_bf16 v[14:17], v[152:155], v[228:231], v[14:17]
	v_mfma_f32_16x16x32_bf16 v[10:13], v[160:163], v[228:231], v[10:13]
	v_mfma_f32_16x16x32_bf16 v[54:57], v[164:167], v[180:183], v[54:57]
	v_mfma_f32_16x16x32_bf16 v[50:53], v[172:175], v[180:183], v[50:53]
	v_mfma_f32_16x16x32_bf16 v[38:41], v[164:167], v[188:191], v[38:41]
	v_mfma_f32_16x16x32_bf16 v[34:37], v[172:175], v[188:191], v[34:37]
	v_mfma_f32_16x16x32_bf16 v[22:25], v[164:167], v[196:199], v[22:25]
	v_mfma_f32_16x16x32_bf16 v[18:21], v[172:175], v[196:199], v[18:21]
	v_mfma_f32_16x16x32_bf16 v[6:9], v[164:167], v[224:227], v[6:9]
	v_mfma_f32_16x16x32_bf16 v[2:5], v[172:175], v[224:227], v[2:5]
	v_mfma_f32_16x16x32_bf16 v[54:57], v[168:171], v[184:187], v[54:57]
	v_mfma_f32_16x16x32_bf16 v[50:53], v[176:179], v[184:187], v[50:53]
	v_mfma_f32_16x16x32_bf16 v[38:41], v[168:171], v[192:195], v[38:41]
	v_mfma_f32_16x16x32_bf16 v[34:37], v[176:179], v[192:195], v[34:37]
	v_mfma_f32_16x16x32_bf16 v[22:25], v[168:171], v[220:223], v[22:25]
	v_mfma_f32_16x16x32_bf16 v[18:21], v[176:179], v[220:223], v[18:21]
	v_mfma_f32_16x16x32_bf16 v[6:9], v[168:171], v[228:231], v[6:9]
	v_mfma_f32_16x16x32_bf16 v[2:5], v[176:179], v[228:231], v[2:5]
	s_barrier
	s_add_i32 s22, s22, 2
	s_add_u32 s14, s14, 0x100
	s_addc_u32 s15, s15, 0
	s_cmpk_gt_u32 s22, 0x7d
	s_mov_b64 s[16:17], s[18:19]
	s_cbranch_scc0 .LBB0_758
	v_lshl_add_u32 v152, s4, 8, v215
	v_lshl_or_b32 v148, s2, 8, v217
	v_ashrrev_i32_e32 v149, 31, v148
	v_ashrrev_i32_e32 v153, 31, v152
	v_or_b32_e32 v176, 16, v152
	v_lshl_add_u64 v[150:151], v[148:149], 1, s[50:51]
	v_lshlrev_b64 v[154:155], 12, v[152:153]
	v_ashrrev_i32_e32 v177, 31, v176
	v_or_b32_e32 v164, 32, v152
	v_lshl_add_u64 v[198:199], v[150:151], 0, v[154:155]
	v_lshlrev_b64 v[154:155], 12, v[176:177]
	v_ashrrev_i32_e32 v165, 31, v164
	v_lshl_add_u64 v[186:187], v[150:151], 0, v[154:155]
	v_lshlrev_b64 v[154:155], 12, v[164:165]
	v_lshl_add_u64 v[174:175], v[150:151], 0, v[154:155]
	v_or_b32_e32 v154, 48, v152
	v_ashrrev_i32_e32 v155, 31, v154
	v_lshlrev_b64 v[156:157], 12, v[154:155]
	v_lshl_add_u64 v[162:163], v[150:151], 0, v[156:157]
	global_load_dwordx2 v[192:193], v[198:199], off
	global_load_dwordx2 v[196:197], v[198:199], off offset:32
	global_load_dwordx2 v[194:195], v[198:199], off offset:256
	global_load_dwordx2 v[190:191], v[198:199], off offset:288
	global_load_dwordx2 v[188:189], v[186:187], off
	global_load_dwordx2 v[184:185], v[186:187], off offset:32
	global_load_dwordx2 v[182:183], v[186:187], off offset:256
	global_load_dwordx2 v[180:181], v[186:187], off offset:288
	global_load_dwordx2 v[178:179], v[174:175], off
	global_load_dwordx2 v[172:173], v[174:175], off offset:32
	global_load_dwordx2 v[170:171], v[174:175], off offset:256
	global_load_dwordx2 v[168:169], v[174:175], off offset:288
	global_load_dwordx2 v[166:167], v[162:163], off
	global_load_dwordx2 v[160:161], v[162:163], off offset:32
	global_load_dwordx2 v[158:159], v[162:163], off offset:256
	global_load_dwordx2 v[156:157], v[162:163], off offset:288
	v_readlane_b32 s4, v244, 52
	v_readlane_b32 s5, v244, 53
	s_mov_b64 s[16:17], -1
	s_andn2_b64 vcc, exec, s[4:5]
	v_cndmask_b32_e64 v200, 0, 1, s[4:5]
	v_cmp_ne_u32_e64 s[44:45], 1, v200
	v_lshlrev_b64 v[200:201], 11, v[152:153]
	v_lshl_add_u64 v[200:201], v[200:201], 0, v[148:149]
	s_waitcnt vmcnt(0)
	v_lshlrev_b32_e32 v220, 16, v192
	v_and_b32_e32 v221, 0xffff0000, v192
	v_lshlrev_b32_e32 v192, 16, v193
	v_and_b32_e32 v193, 0xffff0000, v193
	v_pk_add_f32 v[128:129], v[128:129], v[192:193]
	v_pk_add_f32 v[126:127], v[126:127], v[220:221]
	v_lshl_add_u64 v[192:193], v[200:201], 2, s[48:49]
	s_cbranch_vccnz .LBB0_761
	s_mov_b64 s[16:17], 0
	global_store_dwordx4 v[192:193], v[126:129], off
